# back-edge rotation (loop counter / pointer SALU before the K-loop's last barrier) in the 8 GEMM K-loops, on v49
# baseline (speedup 1.0000x reference)
.LBB0_200:
	ds_read_b128 v[146:149], v174
	ds_read_b128 v[178:181], v174 offset:1024
	ds_read_b128 v[182:185], v174 offset:2048
	ds_read_b128 v[186:189], v174 offset:3072
	ds_read_b128 v[190:193], v175
	ds_read_b128 v[194:197], v175 offset:1024
	ds_read_b128 v[198:201], v175 offset:2048
	ds_read_b128 v[202:205], v175 offset:3072
	s_add_u32 s28, s26, 0xfff80080
	s_addc_u32 s29, s27, -1
	s_cmp_eq_u32 s73, 28
	s_cselect_b32 s31, s19, s29
	s_cselect_b32 s30, s49, s28
	s_cselect_b32 s29, s17, s72
	s_cselect_b32 s28, s50, s51
	v_lshl_add_u64 v[150:151], s[26:27], 0, v[138:139]
	s_add_i32 m0, s25, 0xc000
	ds_read_b128 v[206:209], v176
	ds_read_b128 v[210:213], v176 offset:1024
	ds_read_b128 v[214:217], v176 offset:2048
	ds_read_b128 v[218:221], v176 offset:3072
	ds_read_b128 v[222:225], v176 offset:4096
	ds_read_b128 v[226:229], v176 offset:5120
	ds_read_b128 v[230:233], v176 offset:6144
	ds_read_b128 v[234:237], v176 offset:7168
	global_load_lds_dwordx4 v[150:151], off
	v_lshl_add_u64 v[150:151], s[26:27], 0, v[140:141]
	s_add_i32 m0, s25, 0xe000
	s_nop 0
	global_load_lds_dwordx4 v[150:151], off
	s_waitcnt vmcnt(8)
	s_waitcnt lgkmcnt(0)
	s_barrier
	s_setprio 1
	s_waitcnt lgkmcnt(0)
	v_mfma_i32_16x16x64_i8 v[126:129], v[146:149], v[206:209], v[126:129]
	v_mfma_i32_16x16x64_i8 v[114:117], v[182:185], v[206:209], v[114:117]
	v_mfma_i32_16x16x64_i8 v[122:125], v[146:149], v[214:217], v[122:125]
	v_mfma_i32_16x16x64_i8 v[106:109], v[182:185], v[214:217], v[106:109]
	v_mfma_i32_16x16x64_i8 v[118:121], v[146:149], v[222:225], v[118:121]
	v_mfma_i32_16x16x64_i8 v[102:105], v[182:185], v[222:225], v[102:105]
	v_mfma_i32_16x16x64_i8 v[110:113], v[146:149], v[230:233], v[110:113]
	v_mfma_i32_16x16x64_i8 v[98:101], v[182:185], v[230:233], v[98:101]
	v_mfma_i32_16x16x64_i8 v[126:129], v[178:181], v[210:213], v[126:129]
	v_mfma_i32_16x16x64_i8 v[114:117], v[186:189], v[210:213], v[114:117]
	v_mfma_i32_16x16x64_i8 v[122:125], v[178:181], v[218:221], v[122:125]
	v_mfma_i32_16x16x64_i8 v[106:109], v[186:189], v[218:221], v[106:109]
	v_mfma_i32_16x16x64_i8 v[118:121], v[178:181], v[226:229], v[118:121]
	v_mfma_i32_16x16x64_i8 v[102:105], v[186:189], v[226:229], v[102:105]
	v_mfma_i32_16x16x64_i8 v[110:113], v[178:181], v[234:237], v[110:113]
	v_mfma_i32_16x16x64_i8 v[98:101], v[186:189], v[234:237], v[98:101]
	s_setprio 0
	s_setprio 1
	v_mfma_i32_16x16x64_i8 v[86:89], v[190:193], v[206:209], v[86:89]
	v_mfma_i32_16x16x64_i8 v[46:49], v[198:201], v[206:209], v[46:49]
	v_mfma_i32_16x16x64_i8 v[70:73], v[190:193], v[214:217], v[70:73]
	v_mfma_i32_16x16x64_i8 v[42:45], v[198:201], v[214:217], v[42:45]
	v_mfma_i32_16x16x64_i8 v[62:65], v[190:193], v[222:225], v[62:65]
	v_mfma_i32_16x16x64_i8 v[34:37], v[198:201], v[222:225], v[34:37]
	v_mfma_i32_16x16x64_i8 v[54:57], v[190:193], v[230:233], v[54:57]
	v_mfma_i32_16x16x64_i8 v[26:29], v[198:201], v[230:233], v[26:29]
	v_mfma_i32_16x16x64_i8 v[86:89], v[194:197], v[210:213], v[86:89]
	v_mfma_i32_16x16x64_i8 v[46:49], v[202:205], v[210:213], v[46:49]
	v_mfma_i32_16x16x64_i8 v[70:73], v[194:197], v[218:221], v[70:73]
	v_mfma_i32_16x16x64_i8 v[42:45], v[202:205], v[218:221], v[42:45]
	v_mfma_i32_16x16x64_i8 v[62:65], v[194:197], v[226:229], v[62:65]
	v_mfma_i32_16x16x64_i8 v[34:37], v[202:205], v[226:229], v[34:37]
	v_mfma_i32_16x16x64_i8 v[54:57], v[194:197], v[234:237], v[54:57]
	v_mfma_i32_16x16x64_i8 v[26:29], v[202:205], v[234:237], v[26:29]
	s_setprio 0
	s_barrier
	s_add_i32 s74, s45, s38
	v_lshl_add_u64 v[150:151], s[28:29], 0, v[132:133]
	s_mov_b32 m0, s74
	ds_read_b128 v[206:209], v176 offset:16384
	ds_read_b128 v[210:213], v176 offset:17408
	ds_read_b128 v[214:217], v176 offset:18432
	ds_read_b128 v[218:221], v176 offset:19456
	ds_read_b128 v[222:225], v176 offset:20480
	ds_read_b128 v[226:229], v176 offset:21504
	ds_read_b128 v[230:233], v176 offset:22528
	ds_read_b128 v[234:237], v176 offset:23552
	global_load_lds_dwordx4 v[150:151], off
	s_add_i32 m0, s74, 0x2000
	s_add_u32 s74, s28, 0x80000
	v_lshl_add_u64 v[238:239], s[28:29], 0, v[136:137]
	s_addc_u32 s75, s29, 0
	s_add_i32 s80, s46, s38
	global_load_lds_dwordx4 v[238:239], off
	v_lshl_add_u64 v[240:241], s[74:75], 0, v[132:133]
	s_mov_b32 m0, s80
	v_lshl_add_u64 v[242:243], s[30:31], 0, v[134:135]
	global_load_lds_dwordx4 v[240:241], off
	v_lshl_add_u64 v[240:241], s[74:75], 0, v[136:137]
	s_add_i32 m0, s80, 0x2000
	s_nop 0
	global_load_lds_dwordx4 v[240:241], off
	v_lshl_add_u64 v[240:241], s[30:31], 0, v[130:131]
	s_mov_b32 m0, s25
	s_nop 0
	global_load_lds_dwordx4 v[240:241], off
	s_mov_b32 m0, s39
	s_nop 0
	global_load_lds_dwordx4 v[242:243], off
	s_waitcnt vmcnt(8)
	s_waitcnt lgkmcnt(0)
	s_barrier
	s_setprio 1
	s_waitcnt lgkmcnt(0)
	v_mfma_i32_16x16x64_i8 v[94:97], v[146:149], v[206:209], v[94:97]
	v_mfma_i32_16x16x64_i8 v[78:81], v[182:185], v[206:209], v[78:81]
	v_mfma_i32_16x16x64_i8 v[90:93], v[146:149], v[214:217], v[90:93]
	v_mfma_i32_16x16x64_i8 v[66:69], v[182:185], v[214:217], v[66:69]
	v_mfma_i32_16x16x64_i8 v[82:85], v[146:149], v[222:225], v[82:85]
	v_mfma_i32_16x16x64_i8 v[58:61], v[182:185], v[222:225], v[58:61]
	v_mfma_i32_16x16x64_i8 v[74:77], v[146:149], v[230:233], v[74:77]
	v_mfma_i32_16x16x64_i8 v[50:53], v[182:185], v[230:233], v[50:53]
	v_mfma_i32_16x16x64_i8 v[94:97], v[178:181], v[210:213], v[94:97]
	v_mfma_i32_16x16x64_i8 v[78:81], v[186:189], v[210:213], v[78:81]
	v_mfma_i32_16x16x64_i8 v[90:93], v[178:181], v[218:221], v[90:93]
	v_mfma_i32_16x16x64_i8 v[66:69], v[186:189], v[218:221], v[66:69]
	v_mfma_i32_16x16x64_i8 v[82:85], v[178:181], v[226:229], v[82:85]
	v_mfma_i32_16x16x64_i8 v[58:61], v[186:189], v[226:229], v[58:61]
	v_mfma_i32_16x16x64_i8 v[74:77], v[178:181], v[234:237], v[74:77]
	v_mfma_i32_16x16x64_i8 v[50:53], v[186:189], v[234:237], v[50:53]
	s_setprio 0
	s_setprio 1
	v_mfma_i32_16x16x64_i8 v[38:41], v[190:193], v[206:209], v[38:41]
	v_mfma_i32_16x16x64_i8 v[14:17], v[198:201], v[206:209], v[14:17]
	v_mfma_i32_16x16x64_i8 v[30:33], v[190:193], v[214:217], v[30:33]
	v_mfma_i32_16x16x64_i8 v[10:13], v[198:201], v[214:217], v[10:13]
	v_mfma_i32_16x16x64_i8 v[22:25], v[190:193], v[222:225], v[22:25]
	v_mfma_i32_16x16x64_i8 v[6:9], v[198:201], v[222:225], v[6:9]
	v_mfma_i32_16x16x64_i8 v[18:21], v[190:193], v[230:233], v[18:21]
	v_mfma_i32_16x16x64_i8 v[2:5], v[198:201], v[230:233], v[2:5]
	v_mfma_i32_16x16x64_i8 v[38:41], v[194:197], v[210:213], v[38:41]
	v_mfma_i32_16x16x64_i8 v[14:17], v[202:205], v[210:213], v[14:17]
	v_mfma_i32_16x16x64_i8 v[30:33], v[194:197], v[218:221], v[30:33]
	v_mfma_i32_16x16x64_i8 v[10:13], v[202:205], v[218:221], v[10:13]
	v_mfma_i32_16x16x64_i8 v[22:25], v[194:197], v[226:229], v[22:25]
	v_mfma_i32_16x16x64_i8 v[6:9], v[202:205], v[226:229], v[6:9]
	v_mfma_i32_16x16x64_i8 v[18:21], v[194:197], v[234:237], v[18:21]
	v_mfma_i32_16x16x64_i8 v[2:5], v[202:205], v[234:237], v[2:5]
	s_setprio 0
	s_barrier
	s_add_i32 s74, 0, 0x18000
	v_add_u32_e32 v152, s74, v172
	s_add_i32 s75, 0, 0x1c000
	ds_read_b128 v[146:149], v152
	ds_read_b128 v[178:181], v152 offset:1024
	ds_read_b128 v[182:185], v152 offset:2048
	ds_read_b128 v[186:189], v152 offset:3072
	v_add_u32_e32 v152, s75, v172
	ds_read_b128 v[190:193], v152
	ds_read_b128 v[194:197], v152 offset:1024
	ds_read_b128 v[198:201], v152 offset:2048
	ds_read_b128 v[202:205], v152 offset:3072
	s_add_u32 s30, s30, 0x80000
	s_addc_u32 s31, s31, 0
	s_mov_b32 m0, s40
	v_lshl_add_u64 v[244:245], s[30:31], 0, v[130:131]
	ds_read_b128 v[206:209], v176 offset:32768
	ds_read_b128 v[210:213], v176 offset:33792
	ds_read_b128 v[214:217], v176 offset:34816
	ds_read_b128 v[218:221], v176 offset:35840
	ds_read_b128 v[222:225], v176 offset:36864
	ds_read_b128 v[226:229], v176 offset:37888
	ds_read_b128 v[230:233], v176 offset:38912
	ds_read_b128 v[234:237], v176 offset:39936
	global_load_lds_dwordx4 v[244:245], off
	v_lshl_add_u64 v[244:245], s[30:31], 0, v[134:135]
	s_mov_b32 m0, s41
	s_nop 0
	global_load_lds_dwordx4 v[244:245], off
	s_waitcnt vmcnt(8)
	s_waitcnt lgkmcnt(0)
	s_barrier
	s_setprio 1
	s_waitcnt lgkmcnt(0)
	v_mfma_i32_16x16x64_i8 v[126:129], v[146:149], v[206:209], v[126:129]
	v_mfma_i32_16x16x64_i8 v[114:117], v[182:185], v[206:209], v[114:117]
	v_mfma_i32_16x16x64_i8 v[122:125], v[146:149], v[214:217], v[122:125]
	v_mfma_i32_16x16x64_i8 v[106:109], v[182:185], v[214:217], v[106:109]
	v_mfma_i32_16x16x64_i8 v[118:121], v[146:149], v[222:225], v[118:121]
	v_mfma_i32_16x16x64_i8 v[102:105], v[182:185], v[222:225], v[102:105]
	v_mfma_i32_16x16x64_i8 v[110:113], v[146:149], v[230:233], v[110:113]
	v_mfma_i32_16x16x64_i8 v[98:101], v[182:185], v[230:233], v[98:101]
	v_mfma_i32_16x16x64_i8 v[126:129], v[178:181], v[210:213], v[126:129]
	v_mfma_i32_16x16x64_i8 v[114:117], v[186:189], v[210:213], v[114:117]
	v_mfma_i32_16x16x64_i8 v[122:125], v[178:181], v[218:221], v[122:125]
	v_mfma_i32_16x16x64_i8 v[106:109], v[186:189], v[218:221], v[106:109]
	v_mfma_i32_16x16x64_i8 v[118:121], v[178:181], v[226:229], v[118:121]
	v_mfma_i32_16x16x64_i8 v[102:105], v[186:189], v[226:229], v[102:105]
	v_mfma_i32_16x16x64_i8 v[110:113], v[178:181], v[234:237], v[110:113]
	v_mfma_i32_16x16x64_i8 v[98:101], v[186:189], v[234:237], v[98:101]
	s_setprio 0
	s_setprio 1
	v_mfma_i32_16x16x64_i8 v[86:89], v[190:193], v[206:209], v[86:89]
	v_mfma_i32_16x16x64_i8 v[46:49], v[198:201], v[206:209], v[46:49]
	v_mfma_i32_16x16x64_i8 v[70:73], v[190:193], v[214:217], v[70:73]
	v_mfma_i32_16x16x64_i8 v[42:45], v[198:201], v[214:217], v[42:45]
	v_mfma_i32_16x16x64_i8 v[62:65], v[190:193], v[222:225], v[62:65]
	v_mfma_i32_16x16x64_i8 v[34:37], v[198:201], v[222:225], v[34:37]
	v_mfma_i32_16x16x64_i8 v[54:57], v[190:193], v[230:233], v[54:57]
	v_mfma_i32_16x16x64_i8 v[26:29], v[198:201], v[230:233], v[26:29]
	v_mfma_i32_16x16x64_i8 v[86:89], v[194:197], v[210:213], v[86:89]
	v_mfma_i32_16x16x64_i8 v[46:49], v[202:205], v[210:213], v[46:49]
	v_mfma_i32_16x16x64_i8 v[70:73], v[194:197], v[218:221], v[70:73]
	v_mfma_i32_16x16x64_i8 v[42:45], v[202:205], v[218:221], v[42:45]
	v_mfma_i32_16x16x64_i8 v[62:65], v[194:197], v[226:229], v[62:65]
	v_mfma_i32_16x16x64_i8 v[34:37], v[202:205], v[226:229], v[34:37]
	v_mfma_i32_16x16x64_i8 v[54:57], v[194:197], v[234:237], v[54:57]
	v_mfma_i32_16x16x64_i8 v[26:29], v[202:205], v[234:237], v[26:29]
	s_setprio 0
	s_barrier
	s_add_i32 s30, s74, s38
	v_lshl_add_u64 v[150:151], v[150:151], 0, s[12:13]
	s_mov_b32 m0, s30
	ds_read_b128 v[206:209], v176 offset:49152
	ds_read_b128 v[210:213], v176 offset:50176
	ds_read_b128 v[214:217], v176 offset:51200
	ds_read_b128 v[218:221], v176 offset:52224
	ds_read_b128 v[222:225], v176 offset:53248
	ds_read_b128 v[226:229], v176 offset:54272
	ds_read_b128 v[230:233], v176 offset:55296
	ds_read_b128 v[234:237], v176 offset:56320
	global_load_lds_dwordx4 v[150:151], off
	s_add_i32 m0, s30, 0x2000
	s_add_u32 s28, s28, 0x80080
	v_lshl_add_u64 v[150:151], v[238:239], 0, s[12:13]
	s_addc_u32 s29, s29, 0
	s_add_i32 s30, s75, s38
	global_load_lds_dwordx4 v[150:151], off
	v_lshl_add_u64 v[150:151], s[28:29], 0, v[132:133]
	s_mov_b32 m0, s30
	s_nop 0
	global_load_lds_dwordx4 v[150:151], off
	v_lshl_add_u64 v[150:151], s[28:29], 0, v[136:137]
	s_add_i32 m0, s30, 0x2000
	s_nop 0
	global_load_lds_dwordx4 v[150:151], off
	v_lshl_add_u64 v[150:151], v[240:241], 0, s[12:13]
	s_mov_b32 m0, s43
	s_nop 0
	global_load_lds_dwordx4 v[150:151], off
	v_lshl_add_u64 v[150:151], v[242:243], 0, s[12:13]
	s_mov_b32 m0, s44
	s_nop 0
	global_load_lds_dwordx4 v[150:151], off
	s_waitcnt vmcnt(8)
	s_waitcnt lgkmcnt(0)
	s_barrier
	s_setprio 1
	s_waitcnt lgkmcnt(0)
	v_mfma_i32_16x16x64_i8 v[94:97], v[146:149], v[206:209], v[94:97]
	v_mfma_i32_16x16x64_i8 v[78:81], v[182:185], v[206:209], v[78:81]
	v_mfma_i32_16x16x64_i8 v[90:93], v[146:149], v[214:217], v[90:93]
	v_mfma_i32_16x16x64_i8 v[66:69], v[182:185], v[214:217], v[66:69]
	v_mfma_i32_16x16x64_i8 v[82:85], v[146:149], v[222:225], v[82:85]
	v_mfma_i32_16x16x64_i8 v[58:61], v[182:185], v[222:225], v[58:61]
	v_mfma_i32_16x16x64_i8 v[74:77], v[146:149], v[230:233], v[74:77]
	v_mfma_i32_16x16x64_i8 v[50:53], v[182:185], v[230:233], v[50:53]
	v_mfma_i32_16x16x64_i8 v[94:97], v[178:181], v[210:213], v[94:97]
	v_mfma_i32_16x16x64_i8 v[78:81], v[186:189], v[210:213], v[78:81]
	v_mfma_i32_16x16x64_i8 v[90:93], v[178:181], v[218:221], v[90:93]
	v_mfma_i32_16x16x64_i8 v[66:69], v[186:189], v[218:221], v[66:69]
	v_mfma_i32_16x16x64_i8 v[82:85], v[178:181], v[226:229], v[82:85]
	v_mfma_i32_16x16x64_i8 v[58:61], v[186:189], v[226:229], v[58:61]
	v_mfma_i32_16x16x64_i8 v[74:77], v[178:181], v[234:237], v[74:77]
	v_mfma_i32_16x16x64_i8 v[50:53], v[186:189], v[234:237], v[50:53]
	s_setprio 0
	s_setprio 1
	v_mfma_i32_16x16x64_i8 v[38:41], v[190:193], v[206:209], v[38:41]
	v_mfma_i32_16x16x64_i8 v[14:17], v[198:201], v[206:209], v[14:17]
	v_mfma_i32_16x16x64_i8 v[30:33], v[190:193], v[214:217], v[30:33]
	v_mfma_i32_16x16x64_i8 v[10:13], v[198:201], v[214:217], v[10:13]
	v_mfma_i32_16x16x64_i8 v[22:25], v[190:193], v[222:225], v[22:25]
	v_mfma_i32_16x16x64_i8 v[6:9], v[198:201], v[222:225], v[6:9]
	v_mfma_i32_16x16x64_i8 v[18:21], v[190:193], v[230:233], v[18:21]
	v_mfma_i32_16x16x64_i8 v[2:5], v[198:201], v[230:233], v[2:5]
	v_mfma_i32_16x16x64_i8 v[38:41], v[194:197], v[210:213], v[38:41]
	v_mfma_i32_16x16x64_i8 v[14:17], v[202:205], v[210:213], v[14:17]
	v_mfma_i32_16x16x64_i8 v[30:33], v[194:197], v[218:221], v[30:33]
	v_mfma_i32_16x16x64_i8 v[10:13], v[202:205], v[218:221], v[10:13]
	v_mfma_i32_16x16x64_i8 v[22:25], v[194:197], v[226:229], v[22:25]
	v_mfma_i32_16x16x64_i8 v[6:9], v[202:205], v[226:229], v[6:9]
	v_mfma_i32_16x16x64_i8 v[18:21], v[194:197], v[234:237], v[18:21]
	v_mfma_i32_16x16x64_i8 v[2:5], v[202:205], v[234:237], v[2:5]
	s_setprio 0
	s_add_i32 s73, s73, 2
	s_add_u32 s26, s26, 0x100
	s_addc_u32 s27, s27, 0
	s_add_u32 s51, s51, 0x100
	s_addc_u32 s72, s72, 0
	s_cmp_gt_u32 s73, 29
	s_barrier
	s_cbranch_scc0 .LBB0_200
	s_and_b64 vcc, exec, s[14:15]
	s_cbranch_vccz .LBB0_203
	s_barrier

.LBB0_220:
	ds_read_b128 v[146:149], v1
	ds_read_b128 v[156:159], v1 offset:1024
	ds_read_b128 v[160:163], v1 offset:2048
	ds_read_b128 v[164:167], v1 offset:3072
	ds_read_b128 v[168:171], v153
	ds_read_b128 v[172:175], v153 offset:1024
	ds_read_b128 v[176:179], v153 offset:2048
	ds_read_b128 v[180:183], v153 offset:3072
	s_add_u32 s24, s22, 0xfff00080
	s_addc_u32 s25, s23, -1
	s_cmp_eq_u32 s49, 60
	s_cselect_b32 s27, s15, s25
	s_cselect_b32 s26, s45, s24
	s_cselect_b32 s25, s13, s48
	s_cselect_b32 s24, s46, s47
	v_lshl_add_u64 v[216:217], s[22:23], 0, v[138:139]
	s_add_i32 m0, s21, 0xc000
	ds_read_b128 v[184:187], v154
	ds_read_b128 v[188:191], v154 offset:1024
	ds_read_b128 v[192:195], v154 offset:2048
	ds_read_b128 v[196:199], v154 offset:3072
	ds_read_b128 v[200:203], v154 offset:4096
	ds_read_b128 v[204:207], v154 offset:5120
	ds_read_b128 v[208:211], v154 offset:6144
	ds_read_b128 v[212:215], v154 offset:7168
	global_load_lds_dwordx4 v[216:217], off
	v_lshl_add_u64 v[216:217], s[22:23], 0, v[140:141]
	s_add_i32 m0, s21, 0xe000
	s_nop 0
	global_load_lds_dwordx4 v[216:217], off
	s_waitcnt vmcnt(8)
	s_waitcnt lgkmcnt(0)
	s_barrier
	s_setprio 1
	s_waitcnt lgkmcnt(0)
	v_mfma_f32_16x16x32_bf16 v[126:129], v[146:149], v[184:187], v[126:129]
	v_mfma_f32_16x16x32_bf16 v[122:125], v[160:163], v[184:187], v[122:125]
	v_mfma_f32_16x16x32_bf16 v[118:121], v[146:149], v[192:195], v[118:121]
	v_mfma_f32_16x16x32_bf16 v[110:113], v[160:163], v[192:195], v[110:113]
	v_mfma_f32_16x16x32_bf16 v[102:105], v[146:149], v[200:203], v[102:105]
	v_mfma_f32_16x16x32_bf16 v[94:97], v[160:163], v[200:203], v[94:97]
	v_mfma_f32_16x16x32_bf16 v[86:89], v[146:149], v[208:211], v[86:89]
	v_mfma_f32_16x16x32_bf16 v[78:81], v[160:163], v[208:211], v[78:81]
	v_mfma_f32_16x16x32_bf16 v[126:129], v[156:159], v[188:191], v[126:129]
	v_mfma_f32_16x16x32_bf16 v[122:125], v[164:167], v[188:191], v[122:125]
	v_mfma_f32_16x16x32_bf16 v[118:121], v[156:159], v[196:199], v[118:121]
	v_mfma_f32_16x16x32_bf16 v[110:113], v[164:167], v[196:199], v[110:113]
	v_mfma_f32_16x16x32_bf16 v[102:105], v[156:159], v[204:207], v[102:105]
	v_mfma_f32_16x16x32_bf16 v[94:97], v[164:167], v[204:207], v[94:97]
	v_mfma_f32_16x16x32_bf16 v[86:89], v[156:159], v[212:215], v[86:89]
	v_mfma_f32_16x16x32_bf16 v[78:81], v[164:167], v[212:215], v[78:81]
	s_setprio 0
	s_setprio 1
	v_mfma_f32_16x16x32_bf16 v[114:117], v[168:171], v[184:187], v[114:117]
	v_mfma_f32_16x16x32_bf16 v[106:109], v[176:179], v[184:187], v[106:109]
	v_mfma_f32_16x16x32_bf16 v[98:101], v[168:171], v[192:195], v[98:101]
	v_mfma_f32_16x16x32_bf16 v[90:93], v[176:179], v[192:195], v[90:93]
	v_mfma_f32_16x16x32_bf16 v[82:85], v[168:171], v[200:203], v[82:85]
	v_mfma_f32_16x16x32_bf16 v[74:77], v[176:179], v[200:203], v[74:77]
	v_mfma_f32_16x16x32_bf16 v[70:73], v[168:171], v[208:211], v[70:73]
	v_mfma_f32_16x16x32_bf16 v[66:69], v[176:179], v[208:211], v[66:69]
	v_mfma_f32_16x16x32_bf16 v[114:117], v[172:175], v[188:191], v[114:117]
	v_mfma_f32_16x16x32_bf16 v[106:109], v[180:183], v[188:191], v[106:109]
	v_mfma_f32_16x16x32_bf16 v[98:101], v[172:175], v[196:199], v[98:101]
	v_mfma_f32_16x16x32_bf16 v[90:93], v[180:183], v[196:199], v[90:93]
	v_mfma_f32_16x16x32_bf16 v[82:85], v[172:175], v[204:207], v[82:85]
	v_mfma_f32_16x16x32_bf16 v[74:77], v[180:183], v[204:207], v[74:77]
	v_mfma_f32_16x16x32_bf16 v[70:73], v[172:175], v[212:215], v[70:73]
	v_mfma_f32_16x16x32_bf16 v[66:69], v[180:183], v[212:215], v[66:69]
	s_setprio 0
	s_barrier
	s_add_i32 s50, s41, s28
	v_lshl_add_u64 v[216:217], s[24:25], 0, v[132:133]
	s_mov_b32 m0, s50
	ds_read_b128 v[184:187], v154 offset:16384
	ds_read_b128 v[188:191], v154 offset:17408
	ds_read_b128 v[192:195], v154 offset:18432
	ds_read_b128 v[196:199], v154 offset:19456
	ds_read_b128 v[200:203], v154 offset:20480
	ds_read_b128 v[204:207], v154 offset:21504
	ds_read_b128 v[208:211], v154 offset:22528
	ds_read_b128 v[212:215], v154 offset:23552
	global_load_lds_dwordx4 v[216:217], off
	s_add_i32 m0, s50, 0x2000
	s_add_u32 s50, s24, 0x100000
	v_lshl_add_u64 v[218:219], s[24:25], 0, v[136:137]
	s_addc_u32 s51, s25, 0
	s_add_i32 s72, s42, s28
	global_load_lds_dwordx4 v[218:219], off
	v_lshl_add_u64 v[220:221], s[50:51], 0, v[132:133]
	s_mov_b32 m0, s72
	v_lshl_add_u64 v[222:223], s[26:27], 0, v[134:135]
	global_load_lds_dwordx4 v[220:221], off
	v_lshl_add_u64 v[220:221], s[50:51], 0, v[136:137]
	s_add_i32 m0, s72, 0x2000
	s_nop 0
	global_load_lds_dwordx4 v[220:221], off
	v_lshl_add_u64 v[220:221], s[26:27], 0, v[130:131]
	s_mov_b32 m0, s21
	s_nop 0
	global_load_lds_dwordx4 v[220:221], off
	s_mov_b32 m0, s33
	s_nop 0
	global_load_lds_dwordx4 v[222:223], off
	s_waitcnt vmcnt(8)
	s_waitcnt lgkmcnt(0)
	s_barrier
	s_setprio 1
	s_waitcnt lgkmcnt(0)
	v_mfma_f32_16x16x32_bf16 v[62:65], v[146:149], v[184:187], v[62:65]
	v_mfma_f32_16x16x32_bf16 v[58:61], v[160:163], v[184:187], v[58:61]
	v_mfma_f32_16x16x32_bf16 v[54:57], v[146:149], v[192:195], v[54:57]
	v_mfma_f32_16x16x32_bf16 v[46:49], v[160:163], v[192:195], v[46:49]
	v_mfma_f32_16x16x32_bf16 v[38:41], v[146:149], v[200:203], v[38:41]
	v_mfma_f32_16x16x32_bf16 v[30:33], v[160:163], v[200:203], v[30:33]
	v_mfma_f32_16x16x32_bf16 v[22:25], v[146:149], v[208:211], v[22:25]
	v_mfma_f32_16x16x32_bf16 v[14:17], v[160:163], v[208:211], v[14:17]
	v_mfma_f32_16x16x32_bf16 v[62:65], v[156:159], v[188:191], v[62:65]
	v_mfma_f32_16x16x32_bf16 v[58:61], v[164:167], v[188:191], v[58:61]
	v_mfma_f32_16x16x32_bf16 v[54:57], v[156:159], v[196:199], v[54:57]
	v_mfma_f32_16x16x32_bf16 v[46:49], v[164:167], v[196:199], v[46:49]
	v_mfma_f32_16x16x32_bf16 v[38:41], v[156:159], v[204:207], v[38:41]
	v_mfma_f32_16x16x32_bf16 v[30:33], v[164:167], v[204:207], v[30:33]
	v_mfma_f32_16x16x32_bf16 v[22:25], v[156:159], v[212:215], v[22:25]
	v_mfma_f32_16x16x32_bf16 v[14:17], v[164:167], v[212:215], v[14:17]
	s_setprio 0
	s_setprio 1
	v_mfma_f32_16x16x32_bf16 v[50:53], v[168:171], v[184:187], v[50:53]
	v_mfma_f32_16x16x32_bf16 v[42:45], v[176:179], v[184:187], v[42:45]
	v_mfma_f32_16x16x32_bf16 v[34:37], v[168:171], v[192:195], v[34:37]
	v_mfma_f32_16x16x32_bf16 v[26:29], v[176:179], v[192:195], v[26:29]
	v_mfma_f32_16x16x32_bf16 v[18:21], v[168:171], v[200:203], v[18:21]
	v_mfma_f32_16x16x32_bf16 v[10:13], v[176:179], v[200:203], v[10:13]
	v_mfma_f32_16x16x32_bf16 v[6:9], v[168:171], v[208:211], v[6:9]
	v_mfma_f32_16x16x32_bf16 v[2:5], v[176:179], v[208:211], v[2:5]
	v_mfma_f32_16x16x32_bf16 v[50:53], v[172:175], v[188:191], v[50:53]
	v_mfma_f32_16x16x32_bf16 v[42:45], v[180:183], v[188:191], v[42:45]
	v_mfma_f32_16x16x32_bf16 v[34:37], v[172:175], v[196:199], v[34:37]
	v_mfma_f32_16x16x32_bf16 v[26:29], v[180:183], v[196:199], v[26:29]
	v_mfma_f32_16x16x32_bf16 v[18:21], v[172:175], v[204:207], v[18:21]
	v_mfma_f32_16x16x32_bf16 v[10:13], v[180:183], v[204:207], v[10:13]
	v_mfma_f32_16x16x32_bf16 v[6:9], v[172:175], v[212:215], v[6:9]
	v_mfma_f32_16x16x32_bf16 v[2:5], v[180:183], v[212:215], v[2:5]
	s_setprio 0
	s_barrier
	s_add_i32 s50, 0, 0x18000
	v_add_u32_e32 v155, s50, v151
	s_add_i32 s51, 0, 0x1c000
	ds_read_b128 v[146:149], v155
	ds_read_b128 v[156:159], v155 offset:1024
	ds_read_b128 v[160:163], v155 offset:2048
	ds_read_b128 v[164:167], v155 offset:3072
	v_add_u32_e32 v155, s51, v151
	ds_read_b128 v[168:171], v155
	ds_read_b128 v[172:175], v155 offset:1024
	ds_read_b128 v[176:179], v155 offset:2048
	ds_read_b128 v[180:183], v155 offset:3072
	s_add_u32 s26, s26, 0x100000
	s_addc_u32 s27, s27, 0
	s_mov_b32 m0, s35
	v_lshl_add_u64 v[224:225], s[26:27], 0, v[130:131]
	ds_read_b128 v[184:187], v154 offset:32768
	ds_read_b128 v[188:191], v154 offset:33792
	ds_read_b128 v[192:195], v154 offset:34816
	ds_read_b128 v[196:199], v154 offset:35840
	ds_read_b128 v[200:203], v154 offset:36864
	ds_read_b128 v[204:207], v154 offset:37888
	ds_read_b128 v[208:211], v154 offset:38912
	ds_read_b128 v[212:215], v154 offset:39936
	global_load_lds_dwordx4 v[224:225], off
	v_lshl_add_u64 v[224:225], s[26:27], 0, v[134:135]
	s_mov_b32 m0, s37
	s_nop 0
	global_load_lds_dwordx4 v[224:225], off
	s_waitcnt vmcnt(8)
	s_waitcnt lgkmcnt(0)
	s_barrier
	s_setprio 1
	s_waitcnt lgkmcnt(0)
	v_mfma_f32_16x16x32_bf16 v[126:129], v[146:149], v[184:187], v[126:129]
	v_mfma_f32_16x16x32_bf16 v[122:125], v[160:163], v[184:187], v[122:125]
	v_mfma_f32_16x16x32_bf16 v[118:121], v[146:149], v[192:195], v[118:121]
	v_mfma_f32_16x16x32_bf16 v[110:113], v[160:163], v[192:195], v[110:113]
	v_mfma_f32_16x16x32_bf16 v[102:105], v[146:149], v[200:203], v[102:105]
	v_mfma_f32_16x16x32_bf16 v[94:97], v[160:163], v[200:203], v[94:97]
	v_mfma_f32_16x16x32_bf16 v[86:89], v[146:149], v[208:211], v[86:89]
	v_mfma_f32_16x16x32_bf16 v[78:81], v[160:163], v[208:211], v[78:81]
	v_mfma_f32_16x16x32_bf16 v[126:129], v[156:159], v[188:191], v[126:129]
	v_mfma_f32_16x16x32_bf16 v[122:125], v[164:167], v[188:191], v[122:125]
	v_mfma_f32_16x16x32_bf16 v[118:121], v[156:159], v[196:199], v[118:121]
	v_mfma_f32_16x16x32_bf16 v[110:113], v[164:167], v[196:199], v[110:113]
	v_mfma_f32_16x16x32_bf16 v[102:105], v[156:159], v[204:207], v[102:105]
	v_mfma_f32_16x16x32_bf16 v[94:97], v[164:167], v[204:207], v[94:97]
	v_mfma_f32_16x16x32_bf16 v[86:89], v[156:159], v[212:215], v[86:89]
	v_mfma_f32_16x16x32_bf16 v[78:81], v[164:167], v[212:215], v[78:81]
	s_setprio 0
	s_setprio 1
	v_mfma_f32_16x16x32_bf16 v[114:117], v[168:171], v[184:187], v[114:117]
	v_mfma_f32_16x16x32_bf16 v[106:109], v[176:179], v[184:187], v[106:109]
	v_mfma_f32_16x16x32_bf16 v[98:101], v[168:171], v[192:195], v[98:101]
	v_mfma_f32_16x16x32_bf16 v[90:93], v[176:179], v[192:195], v[90:93]
	v_mfma_f32_16x16x32_bf16 v[82:85], v[168:171], v[200:203], v[82:85]
	v_mfma_f32_16x16x32_bf16 v[74:77], v[176:179], v[200:203], v[74:77]
	v_mfma_f32_16x16x32_bf16 v[70:73], v[168:171], v[208:211], v[70:73]
	v_mfma_f32_16x16x32_bf16 v[66:69], v[176:179], v[208:211], v[66:69]
	v_mfma_f32_16x16x32_bf16 v[114:117], v[172:175], v[188:191], v[114:117]
	v_mfma_f32_16x16x32_bf16 v[106:109], v[180:183], v[188:191], v[106:109]
	v_mfma_f32_16x16x32_bf16 v[98:101], v[172:175], v[196:199], v[98:101]
	v_mfma_f32_16x16x32_bf16 v[90:93], v[180:183], v[196:199], v[90:93]
	v_mfma_f32_16x16x32_bf16 v[82:85], v[172:175], v[204:207], v[82:85]
	v_mfma_f32_16x16x32_bf16 v[74:77], v[180:183], v[204:207], v[74:77]
	v_mfma_f32_16x16x32_bf16 v[70:73], v[172:175], v[212:215], v[70:73]
	v_mfma_f32_16x16x32_bf16 v[66:69], v[180:183], v[212:215], v[66:69]
	s_setprio 0
	s_barrier
	s_add_i32 s26, s50, s28
	v_lshl_add_u64 v[216:217], v[216:217], 0, s[8:9]
	s_mov_b32 m0, s26
	ds_read_b128 v[184:187], v154 offset:49152
	ds_read_b128 v[188:191], v154 offset:50176
	ds_read_b128 v[192:195], v154 offset:51200
	ds_read_b128 v[196:199], v154 offset:52224
	ds_read_b128 v[200:203], v154 offset:53248
	ds_read_b128 v[204:207], v154 offset:54272
	ds_read_b128 v[208:211], v154 offset:55296
	ds_read_b128 v[212:215], v154 offset:56320
	global_load_lds_dwordx4 v[216:217], off
	s_add_i32 m0, s26, 0x2000
	s_add_u32 s24, s24, 0x100080
	v_lshl_add_u64 v[216:217], v[218:219], 0, s[8:9]
	s_addc_u32 s25, s25, 0
	s_add_i32 s26, s51, s28
	global_load_lds_dwordx4 v[216:217], off
	v_lshl_add_u64 v[216:217], s[24:25], 0, v[132:133]
	s_mov_b32 m0, s26
	s_nop 0
	global_load_lds_dwordx4 v[216:217], off
	v_lshl_add_u64 v[216:217], s[24:25], 0, v[136:137]
	s_add_i32 m0, s26, 0x2000
	s_nop 0
	global_load_lds_dwordx4 v[216:217], off
	v_lshl_add_u64 v[216:217], v[220:221], 0, s[8:9]
	s_mov_b32 m0, s39
	s_nop 0
	global_load_lds_dwordx4 v[216:217], off
	v_lshl_add_u64 v[216:217], v[222:223], 0, s[8:9]
	s_mov_b32 m0, s40
	s_nop 0
	global_load_lds_dwordx4 v[216:217], off
	s_waitcnt vmcnt(8)
	s_waitcnt lgkmcnt(0)
	s_barrier
	s_setprio 1
	s_waitcnt lgkmcnt(0)
	v_mfma_f32_16x16x32_bf16 v[62:65], v[146:149], v[184:187], v[62:65]
	v_mfma_f32_16x16x32_bf16 v[58:61], v[160:163], v[184:187], v[58:61]
	v_mfma_f32_16x16x32_bf16 v[54:57], v[146:149], v[192:195], v[54:57]
	v_mfma_f32_16x16x32_bf16 v[46:49], v[160:163], v[192:195], v[46:49]
	v_mfma_f32_16x16x32_bf16 v[38:41], v[146:149], v[200:203], v[38:41]
	v_mfma_f32_16x16x32_bf16 v[30:33], v[160:163], v[200:203], v[30:33]
	v_mfma_f32_16x16x32_bf16 v[22:25], v[146:149], v[208:211], v[22:25]
	v_mfma_f32_16x16x32_bf16 v[14:17], v[160:163], v[208:211], v[14:17]
	v_mfma_f32_16x16x32_bf16 v[62:65], v[156:159], v[188:191], v[62:65]
	v_mfma_f32_16x16x32_bf16 v[58:61], v[164:167], v[188:191], v[58:61]
	v_mfma_f32_16x16x32_bf16 v[54:57], v[156:159], v[196:199], v[54:57]
	v_mfma_f32_16x16x32_bf16 v[46:49], v[164:167], v[196:199], v[46:49]
	v_mfma_f32_16x16x32_bf16 v[38:41], v[156:159], v[204:207], v[38:41]
	v_mfma_f32_16x16x32_bf16 v[30:33], v[164:167], v[204:207], v[30:33]
	v_mfma_f32_16x16x32_bf16 v[22:25], v[156:159], v[212:215], v[22:25]
	v_mfma_f32_16x16x32_bf16 v[14:17], v[164:167], v[212:215], v[14:17]
	s_setprio 0
	s_setprio 1
	v_mfma_f32_16x16x32_bf16 v[50:53], v[168:171], v[184:187], v[50:53]
	v_mfma_f32_16x16x32_bf16 v[42:45], v[176:179], v[184:187], v[42:45]
	v_mfma_f32_16x16x32_bf16 v[34:37], v[168:171], v[192:195], v[34:37]
	v_mfma_f32_16x16x32_bf16 v[26:29], v[176:179], v[192:195], v[26:29]
	v_mfma_f32_16x16x32_bf16 v[18:21], v[168:171], v[200:203], v[18:21]
	v_mfma_f32_16x16x32_bf16 v[10:13], v[176:179], v[200:203], v[10:13]
	v_mfma_f32_16x16x32_bf16 v[6:9], v[168:171], v[208:211], v[6:9]
	v_mfma_f32_16x16x32_bf16 v[2:5], v[176:179], v[208:211], v[2:5]
	v_mfma_f32_16x16x32_bf16 v[50:53], v[172:175], v[188:191], v[50:53]
	v_mfma_f32_16x16x32_bf16 v[42:45], v[180:183], v[188:191], v[42:45]
	v_mfma_f32_16x16x32_bf16 v[34:37], v[172:175], v[196:199], v[34:37]
	v_mfma_f32_16x16x32_bf16 v[26:29], v[180:183], v[196:199], v[26:29]
	v_mfma_f32_16x16x32_bf16 v[18:21], v[172:175], v[204:207], v[18:21]
	v_mfma_f32_16x16x32_bf16 v[10:13], v[180:183], v[204:207], v[10:13]
	v_mfma_f32_16x16x32_bf16 v[6:9], v[172:175], v[212:215], v[6:9]
	v_mfma_f32_16x16x32_bf16 v[2:5], v[180:183], v[212:215], v[2:5]
	s_setprio 0
	s_add_i32 s49, s49, 2
	s_add_u32 s22, s22, 0x100
	s_addc_u32 s23, s23, 0
	s_add_u32 s47, s47, 0x100
	s_addc_u32 s48, s48, 0
	s_cmp_gt_u32 s49, 61
	s_barrier
	s_cbranch_scc0 .LBB0_220
	s_and_b64 vcc, exec, s[10:11]
	s_cbranch_vccz .LBB0_223
	s_barrier

.LBB0_1482:
	ds_read_b128 v[146:149], v157
	ds_read_b128 v[162:165], v157 offset:1024
	ds_read_b128 v[166:169], v157 offset:2048
	ds_read_b128 v[170:173], v157 offset:3072
	ds_read_b128 v[174:177], v159
	ds_read_b128 v[178:181], v159 offset:1024
	ds_read_b128 v[182:185], v159 offset:2048
	ds_read_b128 v[186:189], v159 offset:3072
	s_add_u32 s36, s34, 0xfff80080
	s_addc_u32 s37, s35, -1
	s_cmp_eq_u32 s76, 28
	s_cselect_b32 s39, s25, s37
	s_cselect_b32 s38, s72, s36
	s_cselect_b32 s37, s23, s75
	s_cselect_b32 s36, s73, s74
	v_lshl_add_u64 v[150:151], s[34:35], 0, v[138:139]
	s_add_i32 m0, s31, 0xc000
	ds_read_b128 v[190:193], v161
	ds_read_b128 v[194:197], v161 offset:1024
	ds_read_b128 v[198:201], v161 offset:2048
	ds_read_b128 v[202:205], v161 offset:3072
	ds_read_b128 v[206:209], v161 offset:4096
	ds_read_b128 v[210:213], v161 offset:5120
	ds_read_b128 v[214:217], v161 offset:6144
	ds_read_b128 v[218:221], v161 offset:7168
	global_load_lds_dwordx4 v[150:151], off
	v_lshl_add_u64 v[150:151], s[34:35], 0, v[140:141]
	s_add_i32 m0, s31, 0xe000
	s_nop 0
	global_load_lds_dwordx4 v[150:151], off
	s_waitcnt vmcnt(8)
	s_waitcnt lgkmcnt(0)
	s_barrier
	s_setprio 1
	s_waitcnt lgkmcnt(0)
	v_mfma_i32_16x16x64_i8 v[126:129], v[146:149], v[190:193], v[126:129]
	v_mfma_i32_16x16x64_i8 v[114:117], v[166:169], v[190:193], v[114:117]
	v_mfma_i32_16x16x64_i8 v[122:125], v[146:149], v[198:201], v[122:125]
	v_mfma_i32_16x16x64_i8 v[106:109], v[166:169], v[198:201], v[106:109]
	v_mfma_i32_16x16x64_i8 v[118:121], v[146:149], v[206:209], v[118:121]
	v_mfma_i32_16x16x64_i8 v[102:105], v[166:169], v[206:209], v[102:105]
	v_mfma_i32_16x16x64_i8 v[110:113], v[146:149], v[214:217], v[110:113]
	v_mfma_i32_16x16x64_i8 v[98:101], v[166:169], v[214:217], v[98:101]
	v_mfma_i32_16x16x64_i8 v[126:129], v[162:165], v[194:197], v[126:129]
	v_mfma_i32_16x16x64_i8 v[114:117], v[170:173], v[194:197], v[114:117]
	v_mfma_i32_16x16x64_i8 v[122:125], v[162:165], v[202:205], v[122:125]
	v_mfma_i32_16x16x64_i8 v[106:109], v[170:173], v[202:205], v[106:109]
	v_mfma_i32_16x16x64_i8 v[118:121], v[162:165], v[210:213], v[118:121]
	v_mfma_i32_16x16x64_i8 v[102:105], v[170:173], v[210:213], v[102:105]
	v_mfma_i32_16x16x64_i8 v[110:113], v[162:165], v[218:221], v[110:113]
	v_mfma_i32_16x16x64_i8 v[98:101], v[170:173], v[218:221], v[98:101]
	s_setprio 0
	s_setprio 1
	v_mfma_i32_16x16x64_i8 v[86:89], v[174:177], v[190:193], v[86:89]
	v_mfma_i32_16x16x64_i8 v[46:49], v[182:185], v[190:193], v[46:49]
	v_mfma_i32_16x16x64_i8 v[70:73], v[174:177], v[198:201], v[70:73]
	v_mfma_i32_16x16x64_i8 v[42:45], v[182:185], v[198:201], v[42:45]
	v_mfma_i32_16x16x64_i8 v[62:65], v[174:177], v[206:209], v[62:65]
	v_mfma_i32_16x16x64_i8 v[34:37], v[182:185], v[206:209], v[34:37]
	v_mfma_i32_16x16x64_i8 v[54:57], v[174:177], v[214:217], v[54:57]
	v_mfma_i32_16x16x64_i8 v[26:29], v[182:185], v[214:217], v[26:29]
	v_mfma_i32_16x16x64_i8 v[86:89], v[178:181], v[194:197], v[86:89]
	v_mfma_i32_16x16x64_i8 v[46:49], v[186:189], v[194:197], v[46:49]
	v_mfma_i32_16x16x64_i8 v[70:73], v[178:181], v[202:205], v[70:73]
	v_mfma_i32_16x16x64_i8 v[42:45], v[186:189], v[202:205], v[42:45]
	v_mfma_i32_16x16x64_i8 v[62:65], v[178:181], v[210:213], v[62:65]
	v_mfma_i32_16x16x64_i8 v[34:37], v[186:189], v[210:213], v[34:37]
	v_mfma_i32_16x16x64_i8 v[54:57], v[178:181], v[218:221], v[54:57]
	v_mfma_i32_16x16x64_i8 v[26:29], v[186:189], v[218:221], v[26:29]
	s_setprio 0
	s_barrier
	s_add_i32 s77, s51, s3
	v_lshl_add_u64 v[150:151], s[36:37], 0, v[132:133]
	s_mov_b32 m0, s77
	ds_read_b128 v[190:193], v161 offset:16384
	ds_read_b128 v[194:197], v161 offset:17408
	ds_read_b128 v[198:201], v161 offset:18432
	ds_read_b128 v[202:205], v161 offset:19456
	ds_read_b128 v[206:209], v161 offset:20480
	ds_read_b128 v[210:213], v161 offset:21504
	ds_read_b128 v[214:217], v161 offset:22528
	ds_read_b128 v[218:221], v161 offset:23552
	global_load_lds_dwordx4 v[150:151], off
	s_add_i32 m0, s77, 0x2000
	s_add_u32 s78, s36, 0x80000
	v_lshl_add_u64 v[222:223], s[36:37], 0, v[136:137]
	s_addc_u32 s79, s37, 0
	s_add_i32 s77, s54, s3
	global_load_lds_dwordx4 v[222:223], off
	v_lshl_add_u64 v[224:225], s[78:79], 0, v[132:133]
	s_mov_b32 m0, s77
	v_lshl_add_u64 v[226:227], s[38:39], 0, v[134:135]
	global_load_lds_dwordx4 v[224:225], off
	v_lshl_add_u64 v[224:225], s[78:79], 0, v[136:137]
	s_add_i32 m0, s77, 0x2000
	s_nop 0
	global_load_lds_dwordx4 v[224:225], off
	v_lshl_add_u64 v[224:225], s[38:39], 0, v[130:131]
	s_mov_b32 m0, s31
	s_nop 0
	global_load_lds_dwordx4 v[224:225], off
	s_mov_b32 m0, s45
	s_nop 0
	global_load_lds_dwordx4 v[226:227], off
	s_waitcnt vmcnt(8)
	s_waitcnt lgkmcnt(0)
	s_barrier
	s_setprio 1
	s_waitcnt lgkmcnt(0)
	v_mfma_i32_16x16x64_i8 v[94:97], v[146:149], v[190:193], v[94:97]
	v_mfma_i32_16x16x64_i8 v[78:81], v[166:169], v[190:193], v[78:81]
	v_mfma_i32_16x16x64_i8 v[90:93], v[146:149], v[198:201], v[90:93]
	v_mfma_i32_16x16x64_i8 v[66:69], v[166:169], v[198:201], v[66:69]
	v_mfma_i32_16x16x64_i8 v[82:85], v[146:149], v[206:209], v[82:85]
	v_mfma_i32_16x16x64_i8 v[58:61], v[166:169], v[206:209], v[58:61]
	v_mfma_i32_16x16x64_i8 v[74:77], v[146:149], v[214:217], v[74:77]
	v_mfma_i32_16x16x64_i8 v[50:53], v[166:169], v[214:217], v[50:53]
	v_mfma_i32_16x16x64_i8 v[94:97], v[162:165], v[194:197], v[94:97]
	v_mfma_i32_16x16x64_i8 v[78:81], v[170:173], v[194:197], v[78:81]
	v_mfma_i32_16x16x64_i8 v[90:93], v[162:165], v[202:205], v[90:93]
	v_mfma_i32_16x16x64_i8 v[66:69], v[170:173], v[202:205], v[66:69]
	v_mfma_i32_16x16x64_i8 v[82:85], v[162:165], v[210:213], v[82:85]
	v_mfma_i32_16x16x64_i8 v[58:61], v[170:173], v[210:213], v[58:61]
	v_mfma_i32_16x16x64_i8 v[74:77], v[162:165], v[218:221], v[74:77]
	v_mfma_i32_16x16x64_i8 v[50:53], v[170:173], v[218:221], v[50:53]
	s_setprio 0
	s_setprio 1
	v_mfma_i32_16x16x64_i8 v[38:41], v[174:177], v[190:193], v[38:41]
	v_mfma_i32_16x16x64_i8 v[14:17], v[182:185], v[190:193], v[14:17]
	v_mfma_i32_16x16x64_i8 v[30:33], v[174:177], v[198:201], v[30:33]
	v_mfma_i32_16x16x64_i8 v[10:13], v[182:185], v[198:201], v[10:13]
	v_mfma_i32_16x16x64_i8 v[22:25], v[174:177], v[206:209], v[22:25]
	v_mfma_i32_16x16x64_i8 v[6:9], v[182:185], v[206:209], v[6:9]
	v_mfma_i32_16x16x64_i8 v[18:21], v[174:177], v[214:217], v[18:21]
	v_mfma_i32_16x16x64_i8 v[2:5], v[182:185], v[214:217], v[2:5]
	v_mfma_i32_16x16x64_i8 v[38:41], v[178:181], v[194:197], v[38:41]
	v_mfma_i32_16x16x64_i8 v[14:17], v[186:189], v[194:197], v[14:17]
	v_mfma_i32_16x16x64_i8 v[30:33], v[178:181], v[202:205], v[30:33]
	v_mfma_i32_16x16x64_i8 v[10:13], v[186:189], v[202:205], v[10:13]
	v_mfma_i32_16x16x64_i8 v[22:25], v[178:181], v[210:213], v[22:25]
	v_mfma_i32_16x16x64_i8 v[6:9], v[186:189], v[210:213], v[6:9]
	v_mfma_i32_16x16x64_i8 v[18:21], v[178:181], v[218:221], v[18:21]
	v_mfma_i32_16x16x64_i8 v[2:5], v[186:189], v[218:221], v[2:5]
	s_setprio 0
	s_barrier
	s_add_i32 s77, 0, 0x18000
	v_add_u32_e32 v152, s77, v153
	s_add_i32 s78, 0, 0x1c000
	ds_read_b128 v[146:149], v152
	ds_read_b128 v[162:165], v152 offset:1024
	ds_read_b128 v[166:169], v152 offset:2048
	ds_read_b128 v[170:173], v152 offset:3072
	v_add_u32_e32 v152, s78, v153
	ds_read_b128 v[174:177], v152
	ds_read_b128 v[178:181], v152 offset:1024
	ds_read_b128 v[182:185], v152 offset:2048
	ds_read_b128 v[186:189], v152 offset:3072
	s_add_u32 s38, s38, 0x80000
	s_addc_u32 s39, s39, 0
	s_mov_b32 m0, s46
	v_lshl_add_u64 v[228:229], s[38:39], 0, v[130:131]
	ds_read_b128 v[190:193], v161 offset:32768
	ds_read_b128 v[194:197], v161 offset:33792
	ds_read_b128 v[198:201], v161 offset:34816
	ds_read_b128 v[202:205], v161 offset:35840
	ds_read_b128 v[206:209], v161 offset:36864
	ds_read_b128 v[210:213], v161 offset:37888
	ds_read_b128 v[214:217], v161 offset:38912
	ds_read_b128 v[218:221], v161 offset:39936
	global_load_lds_dwordx4 v[228:229], off
	v_lshl_add_u64 v[228:229], s[38:39], 0, v[134:135]
	s_mov_b32 m0, s47
	s_nop 0
	global_load_lds_dwordx4 v[228:229], off
	s_waitcnt vmcnt(8)
	s_waitcnt lgkmcnt(0)
	s_barrier
	s_setprio 1
	s_waitcnt lgkmcnt(0)
	v_mfma_i32_16x16x64_i8 v[126:129], v[146:149], v[190:193], v[126:129]
	v_mfma_i32_16x16x64_i8 v[114:117], v[166:169], v[190:193], v[114:117]
	v_mfma_i32_16x16x64_i8 v[122:125], v[146:149], v[198:201], v[122:125]
	v_mfma_i32_16x16x64_i8 v[106:109], v[166:169], v[198:201], v[106:109]
	v_mfma_i32_16x16x64_i8 v[118:121], v[146:149], v[206:209], v[118:121]
	v_mfma_i32_16x16x64_i8 v[102:105], v[166:169], v[206:209], v[102:105]
	v_mfma_i32_16x16x64_i8 v[110:113], v[146:149], v[214:217], v[110:113]
	v_mfma_i32_16x16x64_i8 v[98:101], v[166:169], v[214:217], v[98:101]
	v_mfma_i32_16x16x64_i8 v[126:129], v[162:165], v[194:197], v[126:129]
	v_mfma_i32_16x16x64_i8 v[114:117], v[170:173], v[194:197], v[114:117]
	v_mfma_i32_16x16x64_i8 v[122:125], v[162:165], v[202:205], v[122:125]
	v_mfma_i32_16x16x64_i8 v[106:109], v[170:173], v[202:205], v[106:109]
	v_mfma_i32_16x16x64_i8 v[118:121], v[162:165], v[210:213], v[118:121]
	v_mfma_i32_16x16x64_i8 v[102:105], v[170:173], v[210:213], v[102:105]
	v_mfma_i32_16x16x64_i8 v[110:113], v[162:165], v[218:221], v[110:113]
	v_mfma_i32_16x16x64_i8 v[98:101], v[170:173], v[218:221], v[98:101]
	s_setprio 0
	s_setprio 1
	v_mfma_i32_16x16x64_i8 v[86:89], v[174:177], v[190:193], v[86:89]
	v_mfma_i32_16x16x64_i8 v[46:49], v[182:185], v[190:193], v[46:49]
	v_mfma_i32_16x16x64_i8 v[70:73], v[174:177], v[198:201], v[70:73]
	v_mfma_i32_16x16x64_i8 v[42:45], v[182:185], v[198:201], v[42:45]
	v_mfma_i32_16x16x64_i8 v[62:65], v[174:177], v[206:209], v[62:65]
	v_mfma_i32_16x16x64_i8 v[34:37], v[182:185], v[206:209], v[34:37]
	v_mfma_i32_16x16x64_i8 v[54:57], v[174:177], v[214:217], v[54:57]
	v_mfma_i32_16x16x64_i8 v[26:29], v[182:185], v[214:217], v[26:29]
	v_mfma_i32_16x16x64_i8 v[86:89], v[178:181], v[194:197], v[86:89]
	v_mfma_i32_16x16x64_i8 v[46:49], v[186:189], v[194:197], v[46:49]
	v_mfma_i32_16x16x64_i8 v[70:73], v[178:181], v[202:205], v[70:73]
	v_mfma_i32_16x16x64_i8 v[42:45], v[186:189], v[202:205], v[42:45]
	v_mfma_i32_16x16x64_i8 v[62:65], v[178:181], v[210:213], v[62:65]
	v_mfma_i32_16x16x64_i8 v[34:37], v[186:189], v[210:213], v[34:37]
	v_mfma_i32_16x16x64_i8 v[54:57], v[178:181], v[218:221], v[54:57]
	v_mfma_i32_16x16x64_i8 v[26:29], v[186:189], v[218:221], v[26:29]
	s_setprio 0
	s_barrier
	s_add_i32 s38, s77, s3
	v_lshl_add_u64 v[150:151], v[150:151], 0, s[12:13]
	s_mov_b32 m0, s38
	ds_read_b128 v[190:193], v161 offset:49152
	ds_read_b128 v[194:197], v161 offset:50176
	ds_read_b128 v[198:201], v161 offset:51200
	ds_read_b128 v[202:205], v161 offset:52224
	ds_read_b128 v[206:209], v161 offset:53248
	ds_read_b128 v[210:213], v161 offset:54272
	ds_read_b128 v[214:217], v161 offset:55296
	ds_read_b128 v[218:221], v161 offset:56320
	global_load_lds_dwordx4 v[150:151], off
	s_add_i32 m0, s38, 0x2000
	s_add_u32 s36, s36, 0x80080
	v_lshl_add_u64 v[150:151], v[222:223], 0, s[12:13]
	s_addc_u32 s37, s37, 0
	s_add_i32 s38, s78, s3
	global_load_lds_dwordx4 v[150:151], off
	v_lshl_add_u64 v[150:151], s[36:37], 0, v[132:133]
	s_mov_b32 m0, s38
	s_nop 0
	global_load_lds_dwordx4 v[150:151], off
	v_lshl_add_u64 v[150:151], s[36:37], 0, v[136:137]
	s_add_i32 m0, s38, 0x2000
	s_nop 0
	global_load_lds_dwordx4 v[150:151], off
	v_lshl_add_u64 v[150:151], v[224:225], 0, s[12:13]
	s_mov_b32 m0, s49
	s_nop 0
	global_load_lds_dwordx4 v[150:151], off
	v_lshl_add_u64 v[150:151], v[226:227], 0, s[12:13]
	s_mov_b32 m0, s50
	s_nop 0
	global_load_lds_dwordx4 v[150:151], off
	s_waitcnt vmcnt(8)
	s_waitcnt lgkmcnt(0)
	s_barrier
	s_setprio 1
	s_waitcnt lgkmcnt(0)
	v_mfma_i32_16x16x64_i8 v[94:97], v[146:149], v[190:193], v[94:97]
	v_mfma_i32_16x16x64_i8 v[78:81], v[166:169], v[190:193], v[78:81]
	v_mfma_i32_16x16x64_i8 v[90:93], v[146:149], v[198:201], v[90:93]
	v_mfma_i32_16x16x64_i8 v[66:69], v[166:169], v[198:201], v[66:69]
	v_mfma_i32_16x16x64_i8 v[82:85], v[146:149], v[206:209], v[82:85]
	v_mfma_i32_16x16x64_i8 v[58:61], v[166:169], v[206:209], v[58:61]
	v_mfma_i32_16x16x64_i8 v[74:77], v[146:149], v[214:217], v[74:77]
	v_mfma_i32_16x16x64_i8 v[50:53], v[166:169], v[214:217], v[50:53]
	v_mfma_i32_16x16x64_i8 v[94:97], v[162:165], v[194:197], v[94:97]
	v_mfma_i32_16x16x64_i8 v[78:81], v[170:173], v[194:197], v[78:81]
	v_mfma_i32_16x16x64_i8 v[90:93], v[162:165], v[202:205], v[90:93]
	v_mfma_i32_16x16x64_i8 v[66:69], v[170:173], v[202:205], v[66:69]
	v_mfma_i32_16x16x64_i8 v[82:85], v[162:165], v[210:213], v[82:85]
	v_mfma_i32_16x16x64_i8 v[58:61], v[170:173], v[210:213], v[58:61]
	v_mfma_i32_16x16x64_i8 v[74:77], v[162:165], v[218:221], v[74:77]
	v_mfma_i32_16x16x64_i8 v[50:53], v[170:173], v[218:221], v[50:53]
	s_setprio 0
	s_setprio 1
	v_mfma_i32_16x16x64_i8 v[38:41], v[174:177], v[190:193], v[38:41]
	v_mfma_i32_16x16x64_i8 v[14:17], v[182:185], v[190:193], v[14:17]
	v_mfma_i32_16x16x64_i8 v[30:33], v[174:177], v[198:201], v[30:33]
	v_mfma_i32_16x16x64_i8 v[10:13], v[182:185], v[198:201], v[10:13]
	v_mfma_i32_16x16x64_i8 v[22:25], v[174:177], v[206:209], v[22:25]
	v_mfma_i32_16x16x64_i8 v[6:9], v[182:185], v[206:209], v[6:9]
	v_mfma_i32_16x16x64_i8 v[18:21], v[174:177], v[214:217], v[18:21]
	v_mfma_i32_16x16x64_i8 v[2:5], v[182:185], v[214:217], v[2:5]
	v_mfma_i32_16x16x64_i8 v[38:41], v[178:181], v[194:197], v[38:41]
	v_mfma_i32_16x16x64_i8 v[14:17], v[186:189], v[194:197], v[14:17]
	v_mfma_i32_16x16x64_i8 v[30:33], v[178:181], v[202:205], v[30:33]
	v_mfma_i32_16x16x64_i8 v[10:13], v[186:189], v[202:205], v[10:13]
	v_mfma_i32_16x16x64_i8 v[22:25], v[178:181], v[210:213], v[22:25]
	v_mfma_i32_16x16x64_i8 v[6:9], v[186:189], v[210:213], v[6:9]
	v_mfma_i32_16x16x64_i8 v[18:21], v[178:181], v[218:221], v[18:21]
	v_mfma_i32_16x16x64_i8 v[2:5], v[186:189], v[218:221], v[2:5]
	s_setprio 0
	s_add_i32 s76, s76, 2
	s_add_u32 s34, s34, 0x100
	s_addc_u32 s35, s35, 0
	s_add_u32 s74, s74, 0x100
	s_addc_u32 s75, s75, 0
	s_cmp_gt_u32 s76, 29
	s_barrier
	s_cbranch_scc0 .LBB0_1482
	s_and_b64 vcc, exec, s[14:15]
	s_cbranch_vccz .LBB0_1485
	s_barrier

.LBB0_1562:
	ds_read_b128 v[146:149], v152
	ds_read_b128 v[156:159], v152 offset:1024
	ds_read_b128 v[160:163], v152 offset:2048
	ds_read_b128 v[164:167], v152 offset:3072
	ds_read_b128 v[168:171], v153
	ds_read_b128 v[172:175], v153 offset:1024
	ds_read_b128 v[176:179], v153 offset:2048
	ds_read_b128 v[180:183], v153 offset:3072
	s_add_u32 s26, s24, 0xfff80080
	s_addc_u32 s27, s25, -1
	s_cmp_eq_u32 s50, 28
	s_cselect_b32 s29, s17, s27
	s_cselect_b32 s28, s46, s26
	s_cselect_b32 s27, s15, s49
	s_cselect_b32 s26, s47, s48
	v_lshl_add_u64 v[216:217], s[24:25], 0, v[138:139]
	s_add_i32 m0, s23, 0xc000
	ds_read_b128 v[184:187], v154
	ds_read_b128 v[188:191], v154 offset:1024
	ds_read_b128 v[192:195], v154 offset:2048
	ds_read_b128 v[196:199], v154 offset:3072
	ds_read_b128 v[200:203], v154 offset:4096
	ds_read_b128 v[204:207], v154 offset:5120
	ds_read_b128 v[208:211], v154 offset:6144
	ds_read_b128 v[212:215], v154 offset:7168
	global_load_lds_dwordx4 v[216:217], off
	v_lshl_add_u64 v[216:217], s[24:25], 0, v[140:141]
	s_add_i32 m0, s23, 0xe000
	s_nop 0
	global_load_lds_dwordx4 v[216:217], off
	s_waitcnt vmcnt(8)
	s_waitcnt lgkmcnt(0)
	s_barrier
	s_setprio 1
	s_waitcnt lgkmcnt(0)
	v_mfma_f32_16x16x32_bf16 v[126:129], v[146:149], v[184:187], v[126:129]
	v_mfma_f32_16x16x32_bf16 v[122:125], v[160:163], v[184:187], v[122:125]
	v_mfma_f32_16x16x32_bf16 v[114:117], v[146:149], v[192:195], v[114:117]
	v_mfma_f32_16x16x32_bf16 v[106:109], v[160:163], v[192:195], v[106:109]
	v_mfma_f32_16x16x32_bf16 v[98:101], v[146:149], v[200:203], v[98:101]
	v_mfma_f32_16x16x32_bf16 v[90:93], v[160:163], v[200:203], v[90:93]
	v_mfma_f32_16x16x32_bf16 v[82:85], v[146:149], v[208:211], v[82:85]
	v_mfma_f32_16x16x32_bf16 v[74:77], v[160:163], v[208:211], v[74:77]
	v_mfma_f32_16x16x32_bf16 v[126:129], v[156:159], v[188:191], v[126:129]
	v_mfma_f32_16x16x32_bf16 v[122:125], v[164:167], v[188:191], v[122:125]
	v_mfma_f32_16x16x32_bf16 v[114:117], v[156:159], v[196:199], v[114:117]
	v_mfma_f32_16x16x32_bf16 v[106:109], v[164:167], v[196:199], v[106:109]
	v_mfma_f32_16x16x32_bf16 v[98:101], v[156:159], v[204:207], v[98:101]
	v_mfma_f32_16x16x32_bf16 v[90:93], v[164:167], v[204:207], v[90:93]
	v_mfma_f32_16x16x32_bf16 v[82:85], v[156:159], v[212:215], v[82:85]
	v_mfma_f32_16x16x32_bf16 v[74:77], v[164:167], v[212:215], v[74:77]
	s_setprio 0
	s_setprio 1
	v_mfma_f32_16x16x32_bf16 v[118:121], v[168:171], v[184:187], v[118:121]
	v_mfma_f32_16x16x32_bf16 v[110:113], v[176:179], v[184:187], v[110:113]
	v_mfma_f32_16x16x32_bf16 v[102:105], v[168:171], v[192:195], v[102:105]
	v_mfma_f32_16x16x32_bf16 v[94:97], v[176:179], v[192:195], v[94:97]
	v_mfma_f32_16x16x32_bf16 v[86:89], v[168:171], v[200:203], v[86:89]
	v_mfma_f32_16x16x32_bf16 v[78:81], v[176:179], v[200:203], v[78:81]
	v_mfma_f32_16x16x32_bf16 v[70:73], v[168:171], v[208:211], v[70:73]
	v_mfma_f32_16x16x32_bf16 v[66:69], v[176:179], v[208:211], v[66:69]
	v_mfma_f32_16x16x32_bf16 v[118:121], v[172:175], v[188:191], v[118:121]
	v_mfma_f32_16x16x32_bf16 v[110:113], v[180:183], v[188:191], v[110:113]
	v_mfma_f32_16x16x32_bf16 v[102:105], v[172:175], v[196:199], v[102:105]
	v_mfma_f32_16x16x32_bf16 v[94:97], v[180:183], v[196:199], v[94:97]
	v_mfma_f32_16x16x32_bf16 v[86:89], v[172:175], v[204:207], v[86:89]
	v_mfma_f32_16x16x32_bf16 v[78:81], v[180:183], v[204:207], v[78:81]
	v_mfma_f32_16x16x32_bf16 v[70:73], v[172:175], v[212:215], v[70:73]
	v_mfma_f32_16x16x32_bf16 v[66:69], v[180:183], v[212:215], v[66:69]
	s_setprio 0
	s_barrier
	s_add_i32 s51, s43, s35
	v_lshl_add_u64 v[216:217], s[26:27], 0, v[132:133]
	s_mov_b32 m0, s51
	ds_read_b128 v[184:187], v154 offset:16384
	ds_read_b128 v[188:191], v154 offset:17408
	ds_read_b128 v[192:195], v154 offset:18432
	ds_read_b128 v[196:199], v154 offset:19456
	ds_read_b128 v[200:203], v154 offset:20480
	ds_read_b128 v[204:207], v154 offset:21504
	ds_read_b128 v[208:211], v154 offset:22528
	ds_read_b128 v[212:215], v154 offset:23552
	global_load_lds_dwordx4 v[216:217], off
	s_add_i32 m0, s51, 0x2000
	s_add_u32 s54, s26, 0x80000
	v_lshl_add_u64 v[218:219], s[26:27], 0, v[136:137]
	s_addc_u32 s55, s27, 0
	s_add_i32 s51, s44, s35
	global_load_lds_dwordx4 v[218:219], off
	v_lshl_add_u64 v[220:221], s[54:55], 0, v[132:133]
	s_mov_b32 m0, s51
	v_lshl_add_u64 v[222:223], s[28:29], 0, v[134:135]
	global_load_lds_dwordx4 v[220:221], off
	v_lshl_add_u64 v[220:221], s[54:55], 0, v[136:137]
	s_add_i32 m0, s51, 0x2000
	s_nop 0
	global_load_lds_dwordx4 v[220:221], off
	v_lshl_add_u64 v[220:221], s[28:29], 0, v[130:131]
	s_mov_b32 m0, s23
	s_nop 0
	global_load_lds_dwordx4 v[220:221], off
	s_mov_b32 m0, s36
	s_nop 0
	global_load_lds_dwordx4 v[222:223], off
	s_waitcnt vmcnt(8)
	s_waitcnt lgkmcnt(0)
	s_barrier
	s_setprio 1
	s_waitcnt lgkmcnt(0)
	v_mfma_f32_16x16x32_bf16 v[62:65], v[146:149], v[184:187], v[62:65]
	v_mfma_f32_16x16x32_bf16 v[58:61], v[160:163], v[184:187], v[58:61]
	v_mfma_f32_16x16x32_bf16 v[50:53], v[146:149], v[192:195], v[50:53]
	v_mfma_f32_16x16x32_bf16 v[42:45], v[160:163], v[192:195], v[42:45]
	v_mfma_f32_16x16x32_bf16 v[34:37], v[146:149], v[200:203], v[34:37]
	v_mfma_f32_16x16x32_bf16 v[26:29], v[160:163], v[200:203], v[26:29]
	v_mfma_f32_16x16x32_bf16 v[18:21], v[146:149], v[208:211], v[18:21]
	v_mfma_f32_16x16x32_bf16 v[10:13], v[160:163], v[208:211], v[10:13]
	v_mfma_f32_16x16x32_bf16 v[62:65], v[156:159], v[188:191], v[62:65]
	v_mfma_f32_16x16x32_bf16 v[58:61], v[164:167], v[188:191], v[58:61]
	v_mfma_f32_16x16x32_bf16 v[50:53], v[156:159], v[196:199], v[50:53]
	v_mfma_f32_16x16x32_bf16 v[42:45], v[164:167], v[196:199], v[42:45]
	v_mfma_f32_16x16x32_bf16 v[34:37], v[156:159], v[204:207], v[34:37]
	v_mfma_f32_16x16x32_bf16 v[26:29], v[164:167], v[204:207], v[26:29]
	v_mfma_f32_16x16x32_bf16 v[18:21], v[156:159], v[212:215], v[18:21]
	v_mfma_f32_16x16x32_bf16 v[10:13], v[164:167], v[212:215], v[10:13]
	s_setprio 0
	s_setprio 1
	v_mfma_f32_16x16x32_bf16 v[54:57], v[168:171], v[184:187], v[54:57]
	v_mfma_f32_16x16x32_bf16 v[46:49], v[176:179], v[184:187], v[46:49]
	v_mfma_f32_16x16x32_bf16 v[38:41], v[168:171], v[192:195], v[38:41]
	v_mfma_f32_16x16x32_bf16 v[30:33], v[176:179], v[192:195], v[30:33]
	v_mfma_f32_16x16x32_bf16 v[22:25], v[168:171], v[200:203], v[22:25]
	v_mfma_f32_16x16x32_bf16 v[14:17], v[176:179], v[200:203], v[14:17]
	v_mfma_f32_16x16x32_bf16 v[6:9], v[168:171], v[208:211], v[6:9]
	v_mfma_f32_16x16x32_bf16 v[2:5], v[176:179], v[208:211], v[2:5]
	v_mfma_f32_16x16x32_bf16 v[54:57], v[172:175], v[188:191], v[54:57]
	v_mfma_f32_16x16x32_bf16 v[46:49], v[180:183], v[188:191], v[46:49]
	v_mfma_f32_16x16x32_bf16 v[38:41], v[172:175], v[196:199], v[38:41]
	v_mfma_f32_16x16x32_bf16 v[30:33], v[180:183], v[196:199], v[30:33]
	v_mfma_f32_16x16x32_bf16 v[22:25], v[172:175], v[204:207], v[22:25]
	v_mfma_f32_16x16x32_bf16 v[14:17], v[180:183], v[204:207], v[14:17]
	v_mfma_f32_16x16x32_bf16 v[6:9], v[172:175], v[212:215], v[6:9]
	v_mfma_f32_16x16x32_bf16 v[2:5], v[180:183], v[212:215], v[2:5]
	s_setprio 0
	s_barrier
	s_add_i32 s51, 0, 0x18000
	v_add_u32_e32 v155, s51, v150
	s_add_i32 s54, 0, 0x1c000
	ds_read_b128 v[146:149], v155
	ds_read_b128 v[156:159], v155 offset:1024
	ds_read_b128 v[160:163], v155 offset:2048
	ds_read_b128 v[164:167], v155 offset:3072
	v_add_u32_e32 v155, s54, v150
	ds_read_b128 v[168:171], v155
	ds_read_b128 v[172:175], v155 offset:1024
	ds_read_b128 v[176:179], v155 offset:2048
	ds_read_b128 v[180:183], v155 offset:3072
	s_add_u32 s28, s28, 0x80000
	s_addc_u32 s29, s29, 0
	s_mov_b32 m0, s37
	v_lshl_add_u64 v[224:225], s[28:29], 0, v[130:131]
	ds_read_b128 v[184:187], v154 offset:32768
	ds_read_b128 v[188:191], v154 offset:33792
	ds_read_b128 v[192:195], v154 offset:34816
	ds_read_b128 v[196:199], v154 offset:35840
	ds_read_b128 v[200:203], v154 offset:36864
	ds_read_b128 v[204:207], v154 offset:37888
	ds_read_b128 v[208:211], v154 offset:38912
	ds_read_b128 v[212:215], v154 offset:39936
	global_load_lds_dwordx4 v[224:225], off
	v_lshl_add_u64 v[224:225], s[28:29], 0, v[134:135]
	s_mov_b32 m0, s38
	s_nop 0
	global_load_lds_dwordx4 v[224:225], off
	s_waitcnt vmcnt(8)
	s_waitcnt lgkmcnt(0)
	s_barrier
	s_setprio 1
	s_waitcnt lgkmcnt(0)
	v_mfma_f32_16x16x32_bf16 v[126:129], v[146:149], v[184:187], v[126:129]
	v_mfma_f32_16x16x32_bf16 v[122:125], v[160:163], v[184:187], v[122:125]
	v_mfma_f32_16x16x32_bf16 v[114:117], v[146:149], v[192:195], v[114:117]
	v_mfma_f32_16x16x32_bf16 v[106:109], v[160:163], v[192:195], v[106:109]
	v_mfma_f32_16x16x32_bf16 v[98:101], v[146:149], v[200:203], v[98:101]
	v_mfma_f32_16x16x32_bf16 v[90:93], v[160:163], v[200:203], v[90:93]
	v_mfma_f32_16x16x32_bf16 v[82:85], v[146:149], v[208:211], v[82:85]
	v_mfma_f32_16x16x32_bf16 v[74:77], v[160:163], v[208:211], v[74:77]
	v_mfma_f32_16x16x32_bf16 v[126:129], v[156:159], v[188:191], v[126:129]
	v_mfma_f32_16x16x32_bf16 v[122:125], v[164:167], v[188:191], v[122:125]
	v_mfma_f32_16x16x32_bf16 v[114:117], v[156:159], v[196:199], v[114:117]
	v_mfma_f32_16x16x32_bf16 v[106:109], v[164:167], v[196:199], v[106:109]
	v_mfma_f32_16x16x32_bf16 v[98:101], v[156:159], v[204:207], v[98:101]
	v_mfma_f32_16x16x32_bf16 v[90:93], v[164:167], v[204:207], v[90:93]
	v_mfma_f32_16x16x32_bf16 v[82:85], v[156:159], v[212:215], v[82:85]
	v_mfma_f32_16x16x32_bf16 v[74:77], v[164:167], v[212:215], v[74:77]
	s_setprio 0
	s_setprio 1
	v_mfma_f32_16x16x32_bf16 v[118:121], v[168:171], v[184:187], v[118:121]
	v_mfma_f32_16x16x32_bf16 v[110:113], v[176:179], v[184:187], v[110:113]
	v_mfma_f32_16x16x32_bf16 v[102:105], v[168:171], v[192:195], v[102:105]
	v_mfma_f32_16x16x32_bf16 v[94:97], v[176:179], v[192:195], v[94:97]
	v_mfma_f32_16x16x32_bf16 v[86:89], v[168:171], v[200:203], v[86:89]
	v_mfma_f32_16x16x32_bf16 v[78:81], v[176:179], v[200:203], v[78:81]
	v_mfma_f32_16x16x32_bf16 v[70:73], v[168:171], v[208:211], v[70:73]
	v_mfma_f32_16x16x32_bf16 v[66:69], v[176:179], v[208:211], v[66:69]
	v_mfma_f32_16x16x32_bf16 v[118:121], v[172:175], v[188:191], v[118:121]
	v_mfma_f32_16x16x32_bf16 v[110:113], v[180:183], v[188:191], v[110:113]
	v_mfma_f32_16x16x32_bf16 v[102:105], v[172:175], v[196:199], v[102:105]
	v_mfma_f32_16x16x32_bf16 v[94:97], v[180:183], v[196:199], v[94:97]
	v_mfma_f32_16x16x32_bf16 v[86:89], v[172:175], v[204:207], v[86:89]
	v_mfma_f32_16x16x32_bf16 v[78:81], v[180:183], v[204:207], v[78:81]
	v_mfma_f32_16x16x32_bf16 v[70:73], v[172:175], v[212:215], v[70:73]
	v_mfma_f32_16x16x32_bf16 v[66:69], v[180:183], v[212:215], v[66:69]
	s_setprio 0
	s_barrier
	s_add_i32 s28, s51, s35
	v_lshl_add_u64 v[216:217], v[216:217], 0, s[10:11]
	s_mov_b32 m0, s28
	ds_read_b128 v[184:187], v154 offset:49152
	ds_read_b128 v[188:191], v154 offset:50176
	ds_read_b128 v[192:195], v154 offset:51200
	ds_read_b128 v[196:199], v154 offset:52224
	ds_read_b128 v[200:203], v154 offset:53248
	ds_read_b128 v[204:207], v154 offset:54272
	ds_read_b128 v[208:211], v154 offset:55296
	ds_read_b128 v[212:215], v154 offset:56320
	global_load_lds_dwordx4 v[216:217], off
	s_add_i32 m0, s28, 0x2000
	s_add_u32 s26, s26, 0x80080
	v_lshl_add_u64 v[216:217], v[218:219], 0, s[10:11]
	s_addc_u32 s27, s27, 0
	s_add_i32 s28, s54, s35
	global_load_lds_dwordx4 v[216:217], off
	v_lshl_add_u64 v[216:217], s[26:27], 0, v[132:133]
	s_mov_b32 m0, s28
	s_nop 0
	global_load_lds_dwordx4 v[216:217], off
	v_lshl_add_u64 v[216:217], s[26:27], 0, v[136:137]
	s_add_i32 m0, s28, 0x2000
	s_nop 0
	global_load_lds_dwordx4 v[216:217], off
	v_lshl_add_u64 v[216:217], v[220:221], 0, s[10:11]
	s_mov_b32 m0, s41
	s_nop 0
	global_load_lds_dwordx4 v[216:217], off
	v_lshl_add_u64 v[216:217], v[222:223], 0, s[10:11]
	s_mov_b32 m0, s42
	s_nop 0
	global_load_lds_dwordx4 v[216:217], off
	s_waitcnt vmcnt(8)
	s_waitcnt lgkmcnt(0)
	s_barrier
	s_setprio 1
	s_waitcnt lgkmcnt(0)
	v_mfma_f32_16x16x32_bf16 v[62:65], v[146:149], v[184:187], v[62:65]
	v_mfma_f32_16x16x32_bf16 v[58:61], v[160:163], v[184:187], v[58:61]
	v_mfma_f32_16x16x32_bf16 v[50:53], v[146:149], v[192:195], v[50:53]
	v_mfma_f32_16x16x32_bf16 v[42:45], v[160:163], v[192:195], v[42:45]
	v_mfma_f32_16x16x32_bf16 v[34:37], v[146:149], v[200:203], v[34:37]
	v_mfma_f32_16x16x32_bf16 v[26:29], v[160:163], v[200:203], v[26:29]
	v_mfma_f32_16x16x32_bf16 v[18:21], v[146:149], v[208:211], v[18:21]
	v_mfma_f32_16x16x32_bf16 v[10:13], v[160:163], v[208:211], v[10:13]
	v_mfma_f32_16x16x32_bf16 v[62:65], v[156:159], v[188:191], v[62:65]
	v_mfma_f32_16x16x32_bf16 v[58:61], v[164:167], v[188:191], v[58:61]
	v_mfma_f32_16x16x32_bf16 v[50:53], v[156:159], v[196:199], v[50:53]
	v_mfma_f32_16x16x32_bf16 v[42:45], v[164:167], v[196:199], v[42:45]
	v_mfma_f32_16x16x32_bf16 v[34:37], v[156:159], v[204:207], v[34:37]
	v_mfma_f32_16x16x32_bf16 v[26:29], v[164:167], v[204:207], v[26:29]
	v_mfma_f32_16x16x32_bf16 v[18:21], v[156:159], v[212:215], v[18:21]
	v_mfma_f32_16x16x32_bf16 v[10:13], v[164:167], v[212:215], v[10:13]
	s_setprio 0
	s_setprio 1
	v_mfma_f32_16x16x32_bf16 v[54:57], v[168:171], v[184:187], v[54:57]
	v_mfma_f32_16x16x32_bf16 v[46:49], v[176:179], v[184:187], v[46:49]
	v_mfma_f32_16x16x32_bf16 v[38:41], v[168:171], v[192:195], v[38:41]
	v_mfma_f32_16x16x32_bf16 v[30:33], v[176:179], v[192:195], v[30:33]
	v_mfma_f32_16x16x32_bf16 v[22:25], v[168:171], v[200:203], v[22:25]
	v_mfma_f32_16x16x32_bf16 v[14:17], v[176:179], v[200:203], v[14:17]
	v_mfma_f32_16x16x32_bf16 v[6:9], v[168:171], v[208:211], v[6:9]
	v_mfma_f32_16x16x32_bf16 v[2:5], v[176:179], v[208:211], v[2:5]
	v_mfma_f32_16x16x32_bf16 v[54:57], v[172:175], v[188:191], v[54:57]
	v_mfma_f32_16x16x32_bf16 v[46:49], v[180:183], v[188:191], v[46:49]
	v_mfma_f32_16x16x32_bf16 v[38:41], v[172:175], v[196:199], v[38:41]
	v_mfma_f32_16x16x32_bf16 v[30:33], v[180:183], v[196:199], v[30:33]
	v_mfma_f32_16x16x32_bf16 v[22:25], v[172:175], v[204:207], v[22:25]
	v_mfma_f32_16x16x32_bf16 v[14:17], v[180:183], v[204:207], v[14:17]
	v_mfma_f32_16x16x32_bf16 v[6:9], v[172:175], v[212:215], v[6:9]
	v_mfma_f32_16x16x32_bf16 v[2:5], v[180:183], v[212:215], v[2:5]
	s_setprio 0
	s_add_i32 s50, s50, 2
	s_add_u32 s24, s24, 0x100
	s_addc_u32 s25, s25, 0
	s_add_u32 s48, s48, 0x100
	s_addc_u32 s49, s49, 0
	s_cmp_gt_u32 s50, 29
	s_barrier
	s_cbranch_scc0 .LBB0_1562
	s_and_b64 vcc, exec, s[12:13]
	s_cbranch_vccz .LBB0_1565
	s_barrier

.LBB0_1642:
	ds_read_b128 v[146:149], v152
	ds_read_b128 v[156:159], v152 offset:1024
	ds_read_b128 v[160:163], v152 offset:2048
	ds_read_b128 v[164:167], v152 offset:3072
	ds_read_b128 v[168:171], v153
	ds_read_b128 v[172:175], v153 offset:1024
	ds_read_b128 v[176:179], v153 offset:2048
	ds_read_b128 v[180:183], v153 offset:3072
	s_add_u32 s30, s28, 0xfff80080
	s_addc_u32 s31, s29, -1
	s_cmp_eq_u32 s61, 28
	s_cselect_b32 s35, s21, s31
	s_cselect_b32 s34, s51, s30
	s_cselect_b32 s31, s19, s60
	s_cselect_b32 s30, s54, s55
	v_lshl_add_u64 v[216:217], s[28:29], 0, v[138:139]
	s_add_i32 m0, s27, 0xc000
	ds_read_b128 v[184:187], v154
	ds_read_b128 v[188:191], v154 offset:1024
	ds_read_b128 v[192:195], v154 offset:2048
	ds_read_b128 v[196:199], v154 offset:3072
	ds_read_b128 v[200:203], v154 offset:4096
	ds_read_b128 v[204:207], v154 offset:5120
	ds_read_b128 v[208:211], v154 offset:6144
	ds_read_b128 v[212:215], v154 offset:7168
	global_load_lds_dwordx4 v[216:217], off
	v_lshl_add_u64 v[216:217], s[28:29], 0, v[140:141]
	s_add_i32 m0, s27, 0xe000
	s_nop 0
	global_load_lds_dwordx4 v[216:217], off
	s_waitcnt vmcnt(8)
	s_waitcnt lgkmcnt(0)
	s_barrier
	s_setprio 1
	s_waitcnt lgkmcnt(0)
	v_mfma_f32_16x16x32_bf16 v[126:129], v[146:149], v[184:187], v[126:129]
	v_mfma_f32_16x16x32_bf16 v[122:125], v[160:163], v[184:187], v[122:125]
	v_mfma_f32_16x16x32_bf16 v[110:113], v[146:149], v[192:195], v[110:113]
	v_mfma_f32_16x16x32_bf16 v[106:109], v[160:163], v[192:195], v[106:109]
	v_mfma_f32_16x16x32_bf16 v[94:97], v[146:149], v[200:203], v[94:97]
	v_mfma_f32_16x16x32_bf16 v[90:93], v[160:163], v[200:203], v[90:93]
	v_mfma_f32_16x16x32_bf16 v[78:81], v[146:149], v[208:211], v[78:81]
	v_mfma_f32_16x16x32_bf16 v[74:77], v[160:163], v[208:211], v[74:77]
	v_mfma_f32_16x16x32_bf16 v[126:129], v[156:159], v[188:191], v[126:129]
	v_mfma_f32_16x16x32_bf16 v[122:125], v[164:167], v[188:191], v[122:125]
	v_mfma_f32_16x16x32_bf16 v[110:113], v[156:159], v[196:199], v[110:113]
	v_mfma_f32_16x16x32_bf16 v[106:109], v[164:167], v[196:199], v[106:109]
	v_mfma_f32_16x16x32_bf16 v[94:97], v[156:159], v[204:207], v[94:97]
	v_mfma_f32_16x16x32_bf16 v[90:93], v[164:167], v[204:207], v[90:93]
	v_mfma_f32_16x16x32_bf16 v[78:81], v[156:159], v[212:215], v[78:81]
	v_mfma_f32_16x16x32_bf16 v[74:77], v[164:167], v[212:215], v[74:77]
	s_setprio 0
	s_setprio 1
	v_mfma_f32_16x16x32_bf16 v[118:121], v[168:171], v[184:187], v[118:121]
	v_mfma_f32_16x16x32_bf16 v[114:117], v[176:179], v[184:187], v[114:117]
	v_mfma_f32_16x16x32_bf16 v[102:105], v[168:171], v[192:195], v[102:105]
	v_mfma_f32_16x16x32_bf16 v[98:101], v[176:179], v[192:195], v[98:101]
	v_mfma_f32_16x16x32_bf16 v[86:89], v[168:171], v[200:203], v[86:89]
	v_mfma_f32_16x16x32_bf16 v[82:85], v[176:179], v[200:203], v[82:85]
	v_mfma_f32_16x16x32_bf16 v[70:73], v[168:171], v[208:211], v[70:73]
	v_mfma_f32_16x16x32_bf16 v[66:69], v[176:179], v[208:211], v[66:69]
	v_mfma_f32_16x16x32_bf16 v[118:121], v[172:175], v[188:191], v[118:121]
	v_mfma_f32_16x16x32_bf16 v[114:117], v[180:183], v[188:191], v[114:117]
	v_mfma_f32_16x16x32_bf16 v[102:105], v[172:175], v[196:199], v[102:105]
	v_mfma_f32_16x16x32_bf16 v[98:101], v[180:183], v[196:199], v[98:101]
	v_mfma_f32_16x16x32_bf16 v[86:89], v[172:175], v[204:207], v[86:89]
	v_mfma_f32_16x16x32_bf16 v[82:85], v[180:183], v[204:207], v[82:85]
	v_mfma_f32_16x16x32_bf16 v[70:73], v[172:175], v[212:215], v[70:73]
	v_mfma_f32_16x16x32_bf16 v[66:69], v[180:183], v[212:215], v[66:69]
	s_setprio 0
	s_barrier
	s_add_i32 s72, s48, s39
	v_lshl_add_u64 v[216:217], s[30:31], 0, v[132:133]
	s_mov_b32 m0, s72
	ds_read_b128 v[184:187], v154 offset:16384
	ds_read_b128 v[188:191], v154 offset:17408
	ds_read_b128 v[192:195], v154 offset:18432
	ds_read_b128 v[196:199], v154 offset:19456
	ds_read_b128 v[200:203], v154 offset:20480
	ds_read_b128 v[204:207], v154 offset:21504
	ds_read_b128 v[208:211], v154 offset:22528
	ds_read_b128 v[212:215], v154 offset:23552
	global_load_lds_dwordx4 v[216:217], off
	s_add_i32 m0, s72, 0x2000
	s_add_u32 s72, s30, 0x80000
	v_lshl_add_u64 v[218:219], s[30:31], 0, v[136:137]
	s_addc_u32 s73, s31, 0
	s_add_i32 s74, s49, s39
	global_load_lds_dwordx4 v[218:219], off
	v_lshl_add_u64 v[220:221], s[72:73], 0, v[132:133]
	s_mov_b32 m0, s74
	v_lshl_add_u64 v[222:223], s[34:35], 0, v[134:135]
	global_load_lds_dwordx4 v[220:221], off
	v_lshl_add_u64 v[220:221], s[72:73], 0, v[136:137]
	s_add_i32 m0, s74, 0x2000
	s_nop 0
	global_load_lds_dwordx4 v[220:221], off
	v_lshl_add_u64 v[220:221], s[34:35], 0, v[130:131]
	s_mov_b32 m0, s27
	s_nop 0
	global_load_lds_dwordx4 v[220:221], off
	s_mov_b32 m0, s40
	s_nop 0
	global_load_lds_dwordx4 v[222:223], off
	s_waitcnt vmcnt(8)
	s_waitcnt lgkmcnt(0)
	s_barrier
	s_setprio 1
	s_waitcnt lgkmcnt(0)
	v_mfma_f32_16x16x32_bf16 v[62:65], v[146:149], v[184:187], v[62:65]
	v_mfma_f32_16x16x32_bf16 v[58:61], v[160:163], v[184:187], v[58:61]
	v_mfma_f32_16x16x32_bf16 v[46:49], v[146:149], v[192:195], v[46:49]
	v_mfma_f32_16x16x32_bf16 v[42:45], v[160:163], v[192:195], v[42:45]
	v_mfma_f32_16x16x32_bf16 v[30:33], v[146:149], v[200:203], v[30:33]
	v_mfma_f32_16x16x32_bf16 v[26:29], v[160:163], v[200:203], v[26:29]
	v_mfma_f32_16x16x32_bf16 v[14:17], v[146:149], v[208:211], v[14:17]
	v_mfma_f32_16x16x32_bf16 v[10:13], v[160:163], v[208:211], v[10:13]
	v_mfma_f32_16x16x32_bf16 v[62:65], v[156:159], v[188:191], v[62:65]
	v_mfma_f32_16x16x32_bf16 v[58:61], v[164:167], v[188:191], v[58:61]
	v_mfma_f32_16x16x32_bf16 v[46:49], v[156:159], v[196:199], v[46:49]
	v_mfma_f32_16x16x32_bf16 v[42:45], v[164:167], v[196:199], v[42:45]
	v_mfma_f32_16x16x32_bf16 v[30:33], v[156:159], v[204:207], v[30:33]
	v_mfma_f32_16x16x32_bf16 v[26:29], v[164:167], v[204:207], v[26:29]
	v_mfma_f32_16x16x32_bf16 v[14:17], v[156:159], v[212:215], v[14:17]
	v_mfma_f32_16x16x32_bf16 v[10:13], v[164:167], v[212:215], v[10:13]
	s_setprio 0
	s_setprio 1
	v_mfma_f32_16x16x32_bf16 v[54:57], v[168:171], v[184:187], v[54:57]
	v_mfma_f32_16x16x32_bf16 v[50:53], v[176:179], v[184:187], v[50:53]
	v_mfma_f32_16x16x32_bf16 v[38:41], v[168:171], v[192:195], v[38:41]
	v_mfma_f32_16x16x32_bf16 v[34:37], v[176:179], v[192:195], v[34:37]
	v_mfma_f32_16x16x32_bf16 v[22:25], v[168:171], v[200:203], v[22:25]
	v_mfma_f32_16x16x32_bf16 v[18:21], v[176:179], v[200:203], v[18:21]
	v_mfma_f32_16x16x32_bf16 v[6:9], v[168:171], v[208:211], v[6:9]
	v_mfma_f32_16x16x32_bf16 v[2:5], v[176:179], v[208:211], v[2:5]
	v_mfma_f32_16x16x32_bf16 v[54:57], v[172:175], v[188:191], v[54:57]
	v_mfma_f32_16x16x32_bf16 v[50:53], v[180:183], v[188:191], v[50:53]
	v_mfma_f32_16x16x32_bf16 v[38:41], v[172:175], v[196:199], v[38:41]
	v_mfma_f32_16x16x32_bf16 v[34:37], v[180:183], v[196:199], v[34:37]
	v_mfma_f32_16x16x32_bf16 v[22:25], v[172:175], v[204:207], v[22:25]
	v_mfma_f32_16x16x32_bf16 v[18:21], v[180:183], v[204:207], v[18:21]
	v_mfma_f32_16x16x32_bf16 v[6:9], v[172:175], v[212:215], v[6:9]
	v_mfma_f32_16x16x32_bf16 v[2:5], v[180:183], v[212:215], v[2:5]
	s_setprio 0
	s_barrier
	s_add_i32 s72, 0, 0x18000
	v_add_u32_e32 v155, s72, v150
	s_add_i32 s73, 0, 0x1c000
	ds_read_b128 v[146:149], v155
	ds_read_b128 v[156:159], v155 offset:1024
	ds_read_b128 v[160:163], v155 offset:2048
	ds_read_b128 v[164:167], v155 offset:3072
	v_add_u32_e32 v155, s73, v150
	ds_read_b128 v[168:171], v155
	ds_read_b128 v[172:175], v155 offset:1024
	ds_read_b128 v[176:179], v155 offset:2048
	ds_read_b128 v[180:183], v155 offset:3072
	s_add_u32 s34, s34, 0x80000
	s_addc_u32 s35, s35, 0
	s_mov_b32 m0, s41
	v_lshl_add_u64 v[224:225], s[34:35], 0, v[130:131]
	ds_read_b128 v[184:187], v154 offset:32768
	ds_read_b128 v[188:191], v154 offset:33792
	ds_read_b128 v[192:195], v154 offset:34816
	ds_read_b128 v[196:199], v154 offset:35840
	ds_read_b128 v[200:203], v154 offset:36864
	ds_read_b128 v[204:207], v154 offset:37888
	ds_read_b128 v[208:211], v154 offset:38912
	ds_read_b128 v[212:215], v154 offset:39936
	global_load_lds_dwordx4 v[224:225], off
	v_lshl_add_u64 v[224:225], s[34:35], 0, v[134:135]
	s_mov_b32 m0, s42
	s_nop 0
	global_load_lds_dwordx4 v[224:225], off
	s_waitcnt vmcnt(8)
	s_waitcnt lgkmcnt(0)
	s_barrier
	s_setprio 1
	s_waitcnt lgkmcnt(0)
	v_mfma_f32_16x16x32_bf16 v[126:129], v[146:149], v[184:187], v[126:129]
	v_mfma_f32_16x16x32_bf16 v[122:125], v[160:163], v[184:187], v[122:125]
	v_mfma_f32_16x16x32_bf16 v[110:113], v[146:149], v[192:195], v[110:113]
	v_mfma_f32_16x16x32_bf16 v[106:109], v[160:163], v[192:195], v[106:109]
	v_mfma_f32_16x16x32_bf16 v[94:97], v[146:149], v[200:203], v[94:97]
	v_mfma_f32_16x16x32_bf16 v[90:93], v[160:163], v[200:203], v[90:93]
	v_mfma_f32_16x16x32_bf16 v[78:81], v[146:149], v[208:211], v[78:81]
	v_mfma_f32_16x16x32_bf16 v[74:77], v[160:163], v[208:211], v[74:77]
	v_mfma_f32_16x16x32_bf16 v[126:129], v[156:159], v[188:191], v[126:129]
	v_mfma_f32_16x16x32_bf16 v[122:125], v[164:167], v[188:191], v[122:125]
	v_mfma_f32_16x16x32_bf16 v[110:113], v[156:159], v[196:199], v[110:113]
	v_mfma_f32_16x16x32_bf16 v[106:109], v[164:167], v[196:199], v[106:109]
	v_mfma_f32_16x16x32_bf16 v[94:97], v[156:159], v[204:207], v[94:97]
	v_mfma_f32_16x16x32_bf16 v[90:93], v[164:167], v[204:207], v[90:93]
	v_mfma_f32_16x16x32_bf16 v[78:81], v[156:159], v[212:215], v[78:81]
	v_mfma_f32_16x16x32_bf16 v[74:77], v[164:167], v[212:215], v[74:77]
	s_setprio 0
	s_setprio 1
	v_mfma_f32_16x16x32_bf16 v[118:121], v[168:171], v[184:187], v[118:121]
	v_mfma_f32_16x16x32_bf16 v[114:117], v[176:179], v[184:187], v[114:117]
	v_mfma_f32_16x16x32_bf16 v[102:105], v[168:171], v[192:195], v[102:105]
	v_mfma_f32_16x16x32_bf16 v[98:101], v[176:179], v[192:195], v[98:101]
	v_mfma_f32_16x16x32_bf16 v[86:89], v[168:171], v[200:203], v[86:89]
	v_mfma_f32_16x16x32_bf16 v[82:85], v[176:179], v[200:203], v[82:85]
	v_mfma_f32_16x16x32_bf16 v[70:73], v[168:171], v[208:211], v[70:73]
	v_mfma_f32_16x16x32_bf16 v[66:69], v[176:179], v[208:211], v[66:69]
	v_mfma_f32_16x16x32_bf16 v[118:121], v[172:175], v[188:191], v[118:121]
	v_mfma_f32_16x16x32_bf16 v[114:117], v[180:183], v[188:191], v[114:117]
	v_mfma_f32_16x16x32_bf16 v[102:105], v[172:175], v[196:199], v[102:105]
	v_mfma_f32_16x16x32_bf16 v[98:101], v[180:183], v[196:199], v[98:101]
	v_mfma_f32_16x16x32_bf16 v[86:89], v[172:175], v[204:207], v[86:89]
	v_mfma_f32_16x16x32_bf16 v[82:85], v[180:183], v[204:207], v[82:85]
	v_mfma_f32_16x16x32_bf16 v[70:73], v[172:175], v[212:215], v[70:73]
	v_mfma_f32_16x16x32_bf16 v[66:69], v[180:183], v[212:215], v[66:69]
	s_setprio 0
	s_barrier
	s_add_i32 s34, s72, s39
	v_lshl_add_u64 v[216:217], v[216:217], 0, s[12:13]
	s_mov_b32 m0, s34
	ds_read_b128 v[184:187], v154 offset:49152
	ds_read_b128 v[188:191], v154 offset:50176
	ds_read_b128 v[192:195], v154 offset:51200
	ds_read_b128 v[196:199], v154 offset:52224
	ds_read_b128 v[200:203], v154 offset:53248
	ds_read_b128 v[204:207], v154 offset:54272
	ds_read_b128 v[208:211], v154 offset:55296
	ds_read_b128 v[212:215], v154 offset:56320
	global_load_lds_dwordx4 v[216:217], off
	s_add_i32 m0, s34, 0x2000
	s_add_u32 s30, s30, 0x80080
	v_lshl_add_u64 v[216:217], v[218:219], 0, s[12:13]
	s_addc_u32 s31, s31, 0
	s_add_i32 s34, s73, s39
	global_load_lds_dwordx4 v[216:217], off
	v_lshl_add_u64 v[216:217], s[30:31], 0, v[132:133]
	s_mov_b32 m0, s34
	s_nop 0
	global_load_lds_dwordx4 v[216:217], off
	v_lshl_add_u64 v[216:217], s[30:31], 0, v[136:137]
	s_add_i32 m0, s34, 0x2000
	s_nop 0
	global_load_lds_dwordx4 v[216:217], off
	v_lshl_add_u64 v[216:217], v[220:221], 0, s[12:13]
	s_mov_b32 m0, s46
	s_nop 0
	global_load_lds_dwordx4 v[216:217], off
	v_lshl_add_u64 v[216:217], v[222:223], 0, s[12:13]
	s_mov_b32 m0, s47
	s_nop 0
	global_load_lds_dwordx4 v[216:217], off
	s_waitcnt vmcnt(8)
	s_waitcnt lgkmcnt(0)
	s_barrier
	s_setprio 1
	s_waitcnt lgkmcnt(0)
	v_mfma_f32_16x16x32_bf16 v[62:65], v[146:149], v[184:187], v[62:65]
	v_mfma_f32_16x16x32_bf16 v[58:61], v[160:163], v[184:187], v[58:61]
	v_mfma_f32_16x16x32_bf16 v[46:49], v[146:149], v[192:195], v[46:49]
	v_mfma_f32_16x16x32_bf16 v[42:45], v[160:163], v[192:195], v[42:45]
	v_mfma_f32_16x16x32_bf16 v[30:33], v[146:149], v[200:203], v[30:33]
	v_mfma_f32_16x16x32_bf16 v[26:29], v[160:163], v[200:203], v[26:29]
	v_mfma_f32_16x16x32_bf16 v[14:17], v[146:149], v[208:211], v[14:17]
	v_mfma_f32_16x16x32_bf16 v[10:13], v[160:163], v[208:211], v[10:13]
	v_mfma_f32_16x16x32_bf16 v[62:65], v[156:159], v[188:191], v[62:65]
	v_mfma_f32_16x16x32_bf16 v[58:61], v[164:167], v[188:191], v[58:61]
	v_mfma_f32_16x16x32_bf16 v[46:49], v[156:159], v[196:199], v[46:49]
	v_mfma_f32_16x16x32_bf16 v[42:45], v[164:167], v[196:199], v[42:45]
	v_mfma_f32_16x16x32_bf16 v[30:33], v[156:159], v[204:207], v[30:33]
	v_mfma_f32_16x16x32_bf16 v[26:29], v[164:167], v[204:207], v[26:29]
	v_mfma_f32_16x16x32_bf16 v[14:17], v[156:159], v[212:215], v[14:17]
	v_mfma_f32_16x16x32_bf16 v[10:13], v[164:167], v[212:215], v[10:13]
	s_setprio 0
	s_setprio 1
	v_mfma_f32_16x16x32_bf16 v[54:57], v[168:171], v[184:187], v[54:57]
	v_mfma_f32_16x16x32_bf16 v[50:53], v[176:179], v[184:187], v[50:53]
	v_mfma_f32_16x16x32_bf16 v[38:41], v[168:171], v[192:195], v[38:41]
	v_mfma_f32_16x16x32_bf16 v[34:37], v[176:179], v[192:195], v[34:37]
	v_mfma_f32_16x16x32_bf16 v[22:25], v[168:171], v[200:203], v[22:25]
	v_mfma_f32_16x16x32_bf16 v[18:21], v[176:179], v[200:203], v[18:21]
	v_mfma_f32_16x16x32_bf16 v[6:9], v[168:171], v[208:211], v[6:9]
	v_mfma_f32_16x16x32_bf16 v[2:5], v[176:179], v[208:211], v[2:5]
	v_mfma_f32_16x16x32_bf16 v[54:57], v[172:175], v[188:191], v[54:57]
	v_mfma_f32_16x16x32_bf16 v[50:53], v[180:183], v[188:191], v[50:53]
	v_mfma_f32_16x16x32_bf16 v[38:41], v[172:175], v[196:199], v[38:41]
	v_mfma_f32_16x16x32_bf16 v[34:37], v[180:183], v[196:199], v[34:37]
	v_mfma_f32_16x16x32_bf16 v[22:25], v[172:175], v[204:207], v[22:25]
	v_mfma_f32_16x16x32_bf16 v[18:21], v[180:183], v[204:207], v[18:21]
	v_mfma_f32_16x16x32_bf16 v[6:9], v[172:175], v[212:215], v[6:9]
	v_mfma_f32_16x16x32_bf16 v[2:5], v[180:183], v[212:215], v[2:5]
	s_setprio 0
	s_add_i32 s61, s61, 2
	s_add_u32 s28, s28, 0x100
	s_addc_u32 s29, s29, 0
	s_add_u32 s55, s55, 0x100
	s_addc_u32 s60, s60, 0
	s_cmp_gt_u32 s61, 29
	s_barrier
	s_cbranch_scc0 .LBB0_1642
	s_and_b64 vcc, exec, s[14:15]
	s_cbranch_vccz .LBB0_1645
	s_barrier

.LBB0_1722:
	ds_read_b128 v[146:149], v154
	ds_read_b128 v[158:161], v154 offset:1024
	ds_read_b128 v[162:165], v154 offset:2048
	ds_read_b128 v[166:169], v154 offset:3072
	ds_read_b128 v[170:173], v155
	ds_read_b128 v[174:177], v155 offset:1024
	ds_read_b128 v[178:181], v155 offset:2048
	ds_read_b128 v[182:185], v155 offset:3072
	s_add_u32 s34, s30, 0xfff00080
	s_addc_u32 s35, s31, -1
	s_cmp_eq_u32 s72, 60
	s_cselect_b32 s37, s23, s35
	s_cselect_b32 s36, s54, s34
	s_cselect_b32 s35, s21, s61
	s_cselect_b32 s34, s55, s60
	v_lshl_add_u64 v[150:151], s[30:31], 0, v[138:139]
	s_add_i32 m0, s29, 0xc000
	ds_read_b128 v[186:189], v156
	ds_read_b128 v[190:193], v156 offset:1024
	ds_read_b128 v[194:197], v156 offset:2048
	ds_read_b128 v[198:201], v156 offset:3072
	ds_read_b128 v[202:205], v156 offset:4096
	ds_read_b128 v[206:209], v156 offset:5120
	ds_read_b128 v[210:213], v156 offset:6144
	ds_read_b128 v[214:217], v156 offset:7168
	global_load_lds_dwordx4 v[150:151], off
	v_lshl_add_u64 v[150:151], s[30:31], 0, v[140:141]
	s_add_i32 m0, s29, 0xe000
	s_nop 0
	global_load_lds_dwordx4 v[150:151], off
	s_waitcnt vmcnt(8)
	s_waitcnt lgkmcnt(0)
	s_barrier
	s_setprio 1
	s_waitcnt lgkmcnt(0)
	v_mfma_f32_16x16x32_bf16 v[126:129], v[146:149], v[186:189], v[126:129]
	v_mfma_f32_16x16x32_bf16 v[122:125], v[162:165], v[186:189], v[122:125]
	v_mfma_f32_16x16x32_bf16 v[110:113], v[146:149], v[194:197], v[110:113]
	v_mfma_f32_16x16x32_bf16 v[106:109], v[162:165], v[194:197], v[106:109]
	v_mfma_f32_16x16x32_bf16 v[94:97], v[146:149], v[202:205], v[94:97]
	v_mfma_f32_16x16x32_bf16 v[90:93], v[162:165], v[202:205], v[90:93]
	v_mfma_f32_16x16x32_bf16 v[78:81], v[146:149], v[210:213], v[78:81]
	v_mfma_f32_16x16x32_bf16 v[74:77], v[162:165], v[210:213], v[74:77]
	v_mfma_f32_16x16x32_bf16 v[126:129], v[158:161], v[190:193], v[126:129]
	v_mfma_f32_16x16x32_bf16 v[122:125], v[166:169], v[190:193], v[122:125]
	v_mfma_f32_16x16x32_bf16 v[110:113], v[158:161], v[198:201], v[110:113]
	v_mfma_f32_16x16x32_bf16 v[106:109], v[166:169], v[198:201], v[106:109]
	v_mfma_f32_16x16x32_bf16 v[94:97], v[158:161], v[206:209], v[94:97]
	v_mfma_f32_16x16x32_bf16 v[90:93], v[166:169], v[206:209], v[90:93]
	v_mfma_f32_16x16x32_bf16 v[78:81], v[158:161], v[214:217], v[78:81]
	v_mfma_f32_16x16x32_bf16 v[74:77], v[166:169], v[214:217], v[74:77]
	s_setprio 0
	s_setprio 1
	v_mfma_f32_16x16x32_bf16 v[118:121], v[170:173], v[186:189], v[118:121]
	v_mfma_f32_16x16x32_bf16 v[114:117], v[178:181], v[186:189], v[114:117]
	v_mfma_f32_16x16x32_bf16 v[102:105], v[170:173], v[194:197], v[102:105]
	v_mfma_f32_16x16x32_bf16 v[98:101], v[178:181], v[194:197], v[98:101]
	v_mfma_f32_16x16x32_bf16 v[86:89], v[170:173], v[202:205], v[86:89]
	v_mfma_f32_16x16x32_bf16 v[82:85], v[178:181], v[202:205], v[82:85]
	v_mfma_f32_16x16x32_bf16 v[70:73], v[170:173], v[210:213], v[70:73]
	v_mfma_f32_16x16x32_bf16 v[66:69], v[178:181], v[210:213], v[66:69]
	v_mfma_f32_16x16x32_bf16 v[118:121], v[174:177], v[190:193], v[118:121]
	v_mfma_f32_16x16x32_bf16 v[114:117], v[182:185], v[190:193], v[114:117]
	v_mfma_f32_16x16x32_bf16 v[102:105], v[174:177], v[198:201], v[102:105]
	v_mfma_f32_16x16x32_bf16 v[98:101], v[182:185], v[198:201], v[98:101]
	v_mfma_f32_16x16x32_bf16 v[86:89], v[174:177], v[206:209], v[86:89]
	v_mfma_f32_16x16x32_bf16 v[82:85], v[182:185], v[206:209], v[82:85]
	v_mfma_f32_16x16x32_bf16 v[70:73], v[174:177], v[214:217], v[70:73]
	v_mfma_f32_16x16x32_bf16 v[66:69], v[182:185], v[214:217], v[66:69]
	s_setprio 0
	s_barrier
	s_add_i32 s73, s49, s41
	v_lshl_add_u64 v[150:151], s[34:35], 0, v[132:133]
	s_mov_b32 m0, s73
	ds_read_b128 v[186:189], v156 offset:16384
	ds_read_b128 v[190:193], v156 offset:17408
	ds_read_b128 v[194:197], v156 offset:18432
	ds_read_b128 v[198:201], v156 offset:19456
	ds_read_b128 v[202:205], v156 offset:20480
	ds_read_b128 v[206:209], v156 offset:21504
	ds_read_b128 v[210:213], v156 offset:22528
	ds_read_b128 v[214:217], v156 offset:23552
	global_load_lds_dwordx4 v[150:151], off
	s_add_i32 m0, s73, 0x2000
	s_add_u32 s74, s34, 0x100000
	v_lshl_add_u64 v[218:219], s[34:35], 0, v[136:137]
	s_addc_u32 s75, s35, 0
	s_add_i32 s73, s50, s41
	global_load_lds_dwordx4 v[218:219], off
	v_lshl_add_u64 v[220:221], s[74:75], 0, v[132:133]
	s_mov_b32 m0, s73
	v_lshl_add_u64 v[222:223], s[36:37], 0, v[134:135]
	global_load_lds_dwordx4 v[220:221], off
	v_lshl_add_u64 v[220:221], s[74:75], 0, v[136:137]
	s_add_i32 m0, s73, 0x2000
	s_nop 0
	global_load_lds_dwordx4 v[220:221], off
	v_lshl_add_u64 v[220:221], s[36:37], 0, v[130:131]
	s_mov_b32 m0, s29
	s_nop 0
	global_load_lds_dwordx4 v[220:221], off
	s_mov_b32 m0, s42
	s_nop 0
	global_load_lds_dwordx4 v[222:223], off
	s_waitcnt vmcnt(8)
	s_waitcnt lgkmcnt(0)
	s_barrier
	s_setprio 1
	s_waitcnt lgkmcnt(0)
	v_mfma_f32_16x16x32_bf16 v[62:65], v[146:149], v[186:189], v[62:65]
	v_mfma_f32_16x16x32_bf16 v[58:61], v[162:165], v[186:189], v[58:61]
	v_mfma_f32_16x16x32_bf16 v[46:49], v[146:149], v[194:197], v[46:49]
	v_mfma_f32_16x16x32_bf16 v[42:45], v[162:165], v[194:197], v[42:45]
	v_mfma_f32_16x16x32_bf16 v[30:33], v[146:149], v[202:205], v[30:33]
	v_mfma_f32_16x16x32_bf16 v[26:29], v[162:165], v[202:205], v[26:29]
	v_mfma_f32_16x16x32_bf16 v[14:17], v[146:149], v[210:213], v[14:17]
	v_mfma_f32_16x16x32_bf16 v[10:13], v[162:165], v[210:213], v[10:13]
	v_mfma_f32_16x16x32_bf16 v[62:65], v[158:161], v[190:193], v[62:65]
	v_mfma_f32_16x16x32_bf16 v[58:61], v[166:169], v[190:193], v[58:61]
	v_mfma_f32_16x16x32_bf16 v[46:49], v[158:161], v[198:201], v[46:49]
	v_mfma_f32_16x16x32_bf16 v[42:45], v[166:169], v[198:201], v[42:45]
	v_mfma_f32_16x16x32_bf16 v[30:33], v[158:161], v[206:209], v[30:33]
	v_mfma_f32_16x16x32_bf16 v[26:29], v[166:169], v[206:209], v[26:29]
	v_mfma_f32_16x16x32_bf16 v[14:17], v[158:161], v[214:217], v[14:17]
	v_mfma_f32_16x16x32_bf16 v[10:13], v[166:169], v[214:217], v[10:13]
	s_setprio 0
	s_setprio 1
	v_mfma_f32_16x16x32_bf16 v[54:57], v[170:173], v[186:189], v[54:57]
	v_mfma_f32_16x16x32_bf16 v[50:53], v[178:181], v[186:189], v[50:53]
	v_mfma_f32_16x16x32_bf16 v[38:41], v[170:173], v[194:197], v[38:41]
	v_mfma_f32_16x16x32_bf16 v[34:37], v[178:181], v[194:197], v[34:37]
	v_mfma_f32_16x16x32_bf16 v[22:25], v[170:173], v[202:205], v[22:25]
	v_mfma_f32_16x16x32_bf16 v[18:21], v[178:181], v[202:205], v[18:21]
	v_mfma_f32_16x16x32_bf16 v[6:9], v[170:173], v[210:213], v[6:9]
	v_mfma_f32_16x16x32_bf16 v[2:5], v[178:181], v[210:213], v[2:5]
	v_mfma_f32_16x16x32_bf16 v[54:57], v[174:177], v[190:193], v[54:57]
	v_mfma_f32_16x16x32_bf16 v[50:53], v[182:185], v[190:193], v[50:53]
	v_mfma_f32_16x16x32_bf16 v[38:41], v[174:177], v[198:201], v[38:41]
	v_mfma_f32_16x16x32_bf16 v[34:37], v[182:185], v[198:201], v[34:37]
	v_mfma_f32_16x16x32_bf16 v[22:25], v[174:177], v[206:209], v[22:25]
	v_mfma_f32_16x16x32_bf16 v[18:21], v[182:185], v[206:209], v[18:21]
	v_mfma_f32_16x16x32_bf16 v[6:9], v[174:177], v[214:217], v[6:9]
	v_mfma_f32_16x16x32_bf16 v[2:5], v[182:185], v[214:217], v[2:5]
	s_setprio 0
	s_barrier
	s_add_i32 s73, 0, 0x18000
	v_add_u32_e32 v157, s73, v152
	s_add_i32 s74, 0, 0x1c000
	ds_read_b128 v[146:149], v157
	ds_read_b128 v[158:161], v157 offset:1024
	ds_read_b128 v[162:165], v157 offset:2048
	ds_read_b128 v[166:169], v157 offset:3072
	v_add_u32_e32 v157, s74, v152
	ds_read_b128 v[170:173], v157
	ds_read_b128 v[174:177], v157 offset:1024
	ds_read_b128 v[178:181], v157 offset:2048
	ds_read_b128 v[182:185], v157 offset:3072
	s_add_u32 s36, s36, 0x100000
	s_addc_u32 s37, s37, 0
	s_mov_b32 m0, s43
	v_lshl_add_u64 v[224:225], s[36:37], 0, v[130:131]
	ds_read_b128 v[186:189], v156 offset:32768
	ds_read_b128 v[190:193], v156 offset:33792
	ds_read_b128 v[194:197], v156 offset:34816
	ds_read_b128 v[198:201], v156 offset:35840
	ds_read_b128 v[202:205], v156 offset:36864
	ds_read_b128 v[206:209], v156 offset:37888
	ds_read_b128 v[210:213], v156 offset:38912
	ds_read_b128 v[214:217], v156 offset:39936
	global_load_lds_dwordx4 v[224:225], off
	v_lshl_add_u64 v[224:225], s[36:37], 0, v[134:135]
	s_mov_b32 m0, s44
	s_nop 0
	global_load_lds_dwordx4 v[224:225], off
	s_waitcnt vmcnt(8)
	s_waitcnt lgkmcnt(0)
	s_barrier
	s_setprio 1
	s_waitcnt lgkmcnt(0)
	v_mfma_f32_16x16x32_bf16 v[126:129], v[146:149], v[186:189], v[126:129]
	v_mfma_f32_16x16x32_bf16 v[122:125], v[162:165], v[186:189], v[122:125]
	v_mfma_f32_16x16x32_bf16 v[110:113], v[146:149], v[194:197], v[110:113]
	v_mfma_f32_16x16x32_bf16 v[106:109], v[162:165], v[194:197], v[106:109]
	v_mfma_f32_16x16x32_bf16 v[94:97], v[146:149], v[202:205], v[94:97]
	v_mfma_f32_16x16x32_bf16 v[90:93], v[162:165], v[202:205], v[90:93]
	v_mfma_f32_16x16x32_bf16 v[78:81], v[146:149], v[210:213], v[78:81]
	v_mfma_f32_16x16x32_bf16 v[74:77], v[162:165], v[210:213], v[74:77]
	v_mfma_f32_16x16x32_bf16 v[126:129], v[158:161], v[190:193], v[126:129]
	v_mfma_f32_16x16x32_bf16 v[122:125], v[166:169], v[190:193], v[122:125]
	v_mfma_f32_16x16x32_bf16 v[110:113], v[158:161], v[198:201], v[110:113]
	v_mfma_f32_16x16x32_bf16 v[106:109], v[166:169], v[198:201], v[106:109]
	v_mfma_f32_16x16x32_bf16 v[94:97], v[158:161], v[206:209], v[94:97]
	v_mfma_f32_16x16x32_bf16 v[90:93], v[166:169], v[206:209], v[90:93]
	v_mfma_f32_16x16x32_bf16 v[78:81], v[158:161], v[214:217], v[78:81]
	v_mfma_f32_16x16x32_bf16 v[74:77], v[166:169], v[214:217], v[74:77]
	s_setprio 0
	s_setprio 1
	v_mfma_f32_16x16x32_bf16 v[118:121], v[170:173], v[186:189], v[118:121]
	v_mfma_f32_16x16x32_bf16 v[114:117], v[178:181], v[186:189], v[114:117]
	v_mfma_f32_16x16x32_bf16 v[102:105], v[170:173], v[194:197], v[102:105]
	v_mfma_f32_16x16x32_bf16 v[98:101], v[178:181], v[194:197], v[98:101]
	v_mfma_f32_16x16x32_bf16 v[86:89], v[170:173], v[202:205], v[86:89]
	v_mfma_f32_16x16x32_bf16 v[82:85], v[178:181], v[202:205], v[82:85]
	v_mfma_f32_16x16x32_bf16 v[70:73], v[170:173], v[210:213], v[70:73]
	v_mfma_f32_16x16x32_bf16 v[66:69], v[178:181], v[210:213], v[66:69]
	v_mfma_f32_16x16x32_bf16 v[118:121], v[174:177], v[190:193], v[118:121]
	v_mfma_f32_16x16x32_bf16 v[114:117], v[182:185], v[190:193], v[114:117]
	v_mfma_f32_16x16x32_bf16 v[102:105], v[174:177], v[198:201], v[102:105]
	v_mfma_f32_16x16x32_bf16 v[98:101], v[182:185], v[198:201], v[98:101]
	v_mfma_f32_16x16x32_bf16 v[86:89], v[174:177], v[206:209], v[86:89]
	v_mfma_f32_16x16x32_bf16 v[82:85], v[182:185], v[206:209], v[82:85]
	v_mfma_f32_16x16x32_bf16 v[70:73], v[174:177], v[214:217], v[70:73]
	v_mfma_f32_16x16x32_bf16 v[66:69], v[182:185], v[214:217], v[66:69]
	s_setprio 0
	s_barrier
	s_add_i32 s36, s73, s41
	v_lshl_add_u64 v[150:151], v[150:151], 0, s[8:9]
	s_mov_b32 m0, s36
	ds_read_b128 v[186:189], v156 offset:49152
	ds_read_b128 v[190:193], v156 offset:50176
	ds_read_b128 v[194:197], v156 offset:51200
	ds_read_b128 v[198:201], v156 offset:52224
	ds_read_b128 v[202:205], v156 offset:53248
	ds_read_b128 v[206:209], v156 offset:54272
	ds_read_b128 v[210:213], v156 offset:55296
	ds_read_b128 v[214:217], v156 offset:56320
	global_load_lds_dwordx4 v[150:151], off
	s_add_i32 m0, s36, 0x2000
	s_add_u32 s34, s34, 0x100080
	v_lshl_add_u64 v[150:151], v[218:219], 0, s[8:9]
	s_addc_u32 s35, s35, 0
	s_add_i32 s36, s74, s41
	global_load_lds_dwordx4 v[150:151], off
	v_lshl_add_u64 v[150:151], s[34:35], 0, v[132:133]
	s_mov_b32 m0, s36
	s_nop 0
	global_load_lds_dwordx4 v[150:151], off
	v_lshl_add_u64 v[150:151], s[34:35], 0, v[136:137]
	s_add_i32 m0, s36, 0x2000
	s_nop 0
	global_load_lds_dwordx4 v[150:151], off
	v_lshl_add_u64 v[150:151], v[220:221], 0, s[8:9]
	s_mov_b32 m0, s47
	s_nop 0
	global_load_lds_dwordx4 v[150:151], off
	v_lshl_add_u64 v[150:151], v[222:223], 0, s[8:9]
	s_mov_b32 m0, s48
	s_nop 0
	global_load_lds_dwordx4 v[150:151], off
	s_waitcnt vmcnt(8)
	s_waitcnt lgkmcnt(0)
	s_barrier
	s_setprio 1
	s_waitcnt lgkmcnt(0)
	v_mfma_f32_16x16x32_bf16 v[62:65], v[146:149], v[186:189], v[62:65]
	v_mfma_f32_16x16x32_bf16 v[58:61], v[162:165], v[186:189], v[58:61]
	v_mfma_f32_16x16x32_bf16 v[46:49], v[146:149], v[194:197], v[46:49]
	v_mfma_f32_16x16x32_bf16 v[42:45], v[162:165], v[194:197], v[42:45]
	v_mfma_f32_16x16x32_bf16 v[30:33], v[146:149], v[202:205], v[30:33]
	v_mfma_f32_16x16x32_bf16 v[26:29], v[162:165], v[202:205], v[26:29]
	v_mfma_f32_16x16x32_bf16 v[14:17], v[146:149], v[210:213], v[14:17]
	v_mfma_f32_16x16x32_bf16 v[10:13], v[162:165], v[210:213], v[10:13]
	v_mfma_f32_16x16x32_bf16 v[62:65], v[158:161], v[190:193], v[62:65]
	v_mfma_f32_16x16x32_bf16 v[58:61], v[166:169], v[190:193], v[58:61]
	v_mfma_f32_16x16x32_bf16 v[46:49], v[158:161], v[198:201], v[46:49]
	v_mfma_f32_16x16x32_bf16 v[42:45], v[166:169], v[198:201], v[42:45]
	v_mfma_f32_16x16x32_bf16 v[30:33], v[158:161], v[206:209], v[30:33]
	v_mfma_f32_16x16x32_bf16 v[26:29], v[166:169], v[206:209], v[26:29]
	v_mfma_f32_16x16x32_bf16 v[14:17], v[158:161], v[214:217], v[14:17]
	v_mfma_f32_16x16x32_bf16 v[10:13], v[166:169], v[214:217], v[10:13]
	s_setprio 0
	s_setprio 1
	v_mfma_f32_16x16x32_bf16 v[54:57], v[170:173], v[186:189], v[54:57]
	v_mfma_f32_16x16x32_bf16 v[50:53], v[178:181], v[186:189], v[50:53]
	v_mfma_f32_16x16x32_bf16 v[38:41], v[170:173], v[194:197], v[38:41]
	v_mfma_f32_16x16x32_bf16 v[34:37], v[178:181], v[194:197], v[34:37]
	v_mfma_f32_16x16x32_bf16 v[22:25], v[170:173], v[202:205], v[22:25]
	v_mfma_f32_16x16x32_bf16 v[18:21], v[178:181], v[202:205], v[18:21]
	v_mfma_f32_16x16x32_bf16 v[6:9], v[170:173], v[210:213], v[6:9]
	v_mfma_f32_16x16x32_bf16 v[2:5], v[178:181], v[210:213], v[2:5]
	v_mfma_f32_16x16x32_bf16 v[54:57], v[174:177], v[190:193], v[54:57]
	v_mfma_f32_16x16x32_bf16 v[50:53], v[182:185], v[190:193], v[50:53]
	v_mfma_f32_16x16x32_bf16 v[38:41], v[174:177], v[198:201], v[38:41]
	v_mfma_f32_16x16x32_bf16 v[34:37], v[182:185], v[198:201], v[34:37]
	v_mfma_f32_16x16x32_bf16 v[22:25], v[174:177], v[206:209], v[22:25]
	v_mfma_f32_16x16x32_bf16 v[18:21], v[182:185], v[206:209], v[18:21]
	v_mfma_f32_16x16x32_bf16 v[6:9], v[174:177], v[214:217], v[6:9]
	v_mfma_f32_16x16x32_bf16 v[2:5], v[182:185], v[214:217], v[2:5]
	s_setprio 0
	s_add_i32 s72, s72, 2
	s_add_u32 s30, s30, 0x100
	s_addc_u32 s31, s31, 0
	s_add_u32 s60, s60, 0x100
	s_addc_u32 s61, s61, 0
	s_cmp_gt_u32 s72, 61
	s_barrier
	s_cbranch_scc0 .LBB0_1722
	s_and_b64 vcc, exec, s[10:11]
	s_cbranch_vccz .LBB0_1725
	s_barrier

.LBB0_1876:
	ds_read_b128 v[130:133], v219
	ds_read_b128 v[134:137], v219 offset:1024
	ds_read_b128 v[138:141], v219 offset:2048
	ds_read_b128 v[142:145], v219 offset:3072
	ds_read_b128 v[146:149], v220
	ds_read_b128 v[150:153], v220 offset:1024
	ds_read_b128 v[154:157], v220 offset:2048
	ds_read_b128 v[158:161], v220 offset:3072
	s_add_u32 s44, s42, 0xfff80080
	s_addc_u32 s45, s43, -1
	s_cmp_eq_u32 s74, 28
	s_cselect_b32 s47, s31, s45
	s_cselect_b32 s46, s33, s44
	s_cselect_b32 s45, s29, s73
	s_cselect_b32 s44, s39, s41
	v_lshl_add_u64 v[178:179], s[42:43], 0, v[198:199]
	s_add_i32 m0, s51, 0xc000
	ds_read_b128 v[162:165], v221
	ds_read_b128 v[166:169], v221 offset:1024
	ds_read_b128 v[170:173], v221 offset:2048
	ds_read_b128 v[174:177], v221 offset:3072
	ds_read_b128 v[206:209], v221 offset:4096
	ds_read_b128 v[210:213], v221 offset:5120
	ds_read_b128 v[224:227], v221 offset:6144
	ds_read_b128 v[228:231], v221 offset:7168
	global_load_lds_dwordx4 v[178:179], off
	v_lshl_add_u64 v[178:179], s[42:43], 0, v[200:201]
	s_add_i32 m0, s51, 0xe000
	s_nop 0
	global_load_lds_dwordx4 v[178:179], off
	s_waitcnt vmcnt(8)
	s_waitcnt lgkmcnt(0)
	s_barrier
	s_setprio 1
	s_waitcnt lgkmcnt(0)
	v_mfma_i32_16x16x64_i8 v[126:129], v[130:133], v[162:165], v[126:129]
	v_mfma_i32_16x16x64_i8 v[62:65], v[138:141], v[162:165], v[62:65]
	v_mfma_i32_16x16x64_i8 v[118:121], v[130:133], v[170:173], v[118:121]
	v_mfma_i32_16x16x64_i8 v[54:57], v[138:141], v[170:173], v[54:57]
	v_mfma_i32_16x16x64_i8 v[110:113], v[130:133], v[206:209], v[110:113]
	v_mfma_i32_16x16x64_i8 v[46:49], v[138:141], v[206:209], v[46:49]
	v_mfma_i32_16x16x64_i8 v[102:105], v[130:133], v[224:227], v[102:105]
	v_mfma_i32_16x16x64_i8 v[38:41], v[138:141], v[224:227], v[38:41]
	v_mfma_i32_16x16x64_i8 v[126:129], v[134:137], v[166:169], v[126:129]
	v_mfma_i32_16x16x64_i8 v[62:65], v[142:145], v[166:169], v[62:65]
	v_mfma_i32_16x16x64_i8 v[118:121], v[134:137], v[174:177], v[118:121]
	v_mfma_i32_16x16x64_i8 v[54:57], v[142:145], v[174:177], v[54:57]
	v_mfma_i32_16x16x64_i8 v[110:113], v[134:137], v[210:213], v[110:113]
	v_mfma_i32_16x16x64_i8 v[46:49], v[142:145], v[210:213], v[46:49]
	v_mfma_i32_16x16x64_i8 v[102:105], v[134:137], v[228:231], v[102:105]
	v_mfma_i32_16x16x64_i8 v[38:41], v[142:145], v[228:231], v[38:41]
	s_setprio 0
	s_setprio 1
	v_mfma_i32_16x16x64_i8 v[122:125], v[146:149], v[162:165], v[122:125]
	v_mfma_i32_16x16x64_i8 v[58:61], v[154:157], v[162:165], v[58:61]
	v_mfma_i32_16x16x64_i8 v[114:117], v[146:149], v[170:173], v[114:117]
	v_mfma_i32_16x16x64_i8 v[50:53], v[154:157], v[170:173], v[50:53]
	v_mfma_i32_16x16x64_i8 v[106:109], v[146:149], v[206:209], v[106:109]
	v_mfma_i32_16x16x64_i8 v[42:45], v[154:157], v[206:209], v[42:45]
	v_mfma_i32_16x16x64_i8 v[98:101], v[146:149], v[224:227], v[98:101]
	v_mfma_i32_16x16x64_i8 v[34:37], v[154:157], v[224:227], v[34:37]
	v_mfma_i32_16x16x64_i8 v[122:125], v[150:153], v[166:169], v[122:125]
	v_mfma_i32_16x16x64_i8 v[58:61], v[158:161], v[166:169], v[58:61]
	v_mfma_i32_16x16x64_i8 v[114:117], v[150:153], v[174:177], v[114:117]
	v_mfma_i32_16x16x64_i8 v[50:53], v[158:161], v[174:177], v[50:53]
	v_mfma_i32_16x16x64_i8 v[106:109], v[150:153], v[210:213], v[106:109]
	v_mfma_i32_16x16x64_i8 v[42:45], v[158:161], v[210:213], v[42:45]
	v_mfma_i32_16x16x64_i8 v[98:101], v[150:153], v[228:231], v[98:101]
	v_mfma_i32_16x16x64_i8 v[34:37], v[158:161], v[228:231], v[34:37]
	s_setprio 0
	s_barrier
	s_add_i32 s75, s69, s50
	v_lshl_add_u64 v[178:179], s[44:45], 0, v[182:183]
	s_mov_b32 m0, s75
	ds_read_b128 v[162:165], v221 offset:16384
	ds_read_b128 v[166:169], v221 offset:17408
	ds_read_b128 v[170:173], v221 offset:18432
	ds_read_b128 v[174:177], v221 offset:19456
	ds_read_b128 v[206:209], v221 offset:20480
	ds_read_b128 v[210:213], v221 offset:21504
	ds_read_b128 v[224:227], v221 offset:22528
	ds_read_b128 v[228:231], v221 offset:23552
	global_load_lds_dwordx4 v[178:179], off
	s_add_i32 m0, s75, 0x2000
	s_add_u32 s76, s44, 0x80000
	v_lshl_add_u64 v[232:233], s[44:45], 0, v[186:187]
	s_addc_u32 s77, s45, 0
	s_add_i32 s75, s70, s50
	global_load_lds_dwordx4 v[232:233], off
	v_lshl_add_u64 v[234:235], s[76:77], 0, v[182:183]
	s_mov_b32 m0, s75
	v_lshl_add_u64 v[236:237], s[46:47], 0, v[184:185]
	global_load_lds_dwordx4 v[234:235], off
	v_lshl_add_u64 v[234:235], s[76:77], 0, v[186:187]
	s_add_i32 m0, s75, 0x2000
	s_nop 0
	global_load_lds_dwordx4 v[234:235], off
	v_lshl_add_u64 v[234:235], s[46:47], 0, v[180:181]
	s_mov_b32 m0, s51
	s_nop 0
	global_load_lds_dwordx4 v[234:235], off
	s_mov_b32 m0, s52
	s_nop 0
	global_load_lds_dwordx4 v[236:237], off
	s_waitcnt vmcnt(8)
	s_waitcnt lgkmcnt(0)
	s_barrier
	s_setprio 1
	s_waitcnt lgkmcnt(0)
	v_mfma_i32_16x16x64_i8 v[94:97], v[130:133], v[162:165], v[94:97]
	v_mfma_i32_16x16x64_i8 v[30:33], v[138:141], v[162:165], v[30:33]
	v_mfma_i32_16x16x64_i8 v[86:89], v[130:133], v[170:173], v[86:89]
	v_mfma_i32_16x16x64_i8 v[22:25], v[138:141], v[170:173], v[22:25]
	v_mfma_i32_16x16x64_i8 v[78:81], v[130:133], v[206:209], v[78:81]
	v_mfma_i32_16x16x64_i8 v[14:17], v[138:141], v[206:209], v[14:17]
	v_mfma_i32_16x16x64_i8 v[70:73], v[130:133], v[224:227], v[70:73]
	v_mfma_i32_16x16x64_i8 v[6:9], v[138:141], v[224:227], v[6:9]
	v_mfma_i32_16x16x64_i8 v[94:97], v[134:137], v[166:169], v[94:97]
	v_mfma_i32_16x16x64_i8 v[30:33], v[142:145], v[166:169], v[30:33]
	v_mfma_i32_16x16x64_i8 v[86:89], v[134:137], v[174:177], v[86:89]
	v_mfma_i32_16x16x64_i8 v[22:25], v[142:145], v[174:177], v[22:25]
	v_mfma_i32_16x16x64_i8 v[78:81], v[134:137], v[210:213], v[78:81]
	v_mfma_i32_16x16x64_i8 v[14:17], v[142:145], v[210:213], v[14:17]
	v_mfma_i32_16x16x64_i8 v[70:73], v[134:137], v[228:231], v[70:73]
	v_mfma_i32_16x16x64_i8 v[6:9], v[142:145], v[228:231], v[6:9]
	s_setprio 0
	s_setprio 1
	v_mfma_i32_16x16x64_i8 v[90:93], v[146:149], v[162:165], v[90:93]
	v_mfma_i32_16x16x64_i8 v[26:29], v[154:157], v[162:165], v[26:29]
	v_mfma_i32_16x16x64_i8 v[82:85], v[146:149], v[170:173], v[82:85]
	v_mfma_i32_16x16x64_i8 v[18:21], v[154:157], v[170:173], v[18:21]
	v_mfma_i32_16x16x64_i8 v[74:77], v[146:149], v[206:209], v[74:77]
	v_mfma_i32_16x16x64_i8 v[10:13], v[154:157], v[206:209], v[10:13]
	v_mfma_i32_16x16x64_i8 v[66:69], v[146:149], v[224:227], v[66:69]
	v_mfma_i32_16x16x64_i8 v[2:5], v[154:157], v[224:227], v[2:5]
	v_mfma_i32_16x16x64_i8 v[90:93], v[150:153], v[166:169], v[90:93]
	v_mfma_i32_16x16x64_i8 v[26:29], v[158:161], v[166:169], v[26:29]
	v_mfma_i32_16x16x64_i8 v[82:85], v[150:153], v[174:177], v[82:85]
	v_mfma_i32_16x16x64_i8 v[18:21], v[158:161], v[174:177], v[18:21]
	v_mfma_i32_16x16x64_i8 v[74:77], v[150:153], v[210:213], v[74:77]
	v_mfma_i32_16x16x64_i8 v[10:13], v[158:161], v[210:213], v[10:13]
	v_mfma_i32_16x16x64_i8 v[66:69], v[150:153], v[228:231], v[66:69]
	v_mfma_i32_16x16x64_i8 v[2:5], v[158:161], v[228:231], v[2:5]
	s_setprio 0
	s_barrier
	s_add_i32 s75, 0, 0x18000
	s_add_i32 s76, 0, 0x1c000
	v_add_u32_e32 v142, s75, v191
	v_add_u32_e32 v158, s76, v191
	ds_read_b128 v[130:133], v142
	ds_read_b128 v[134:137], v142 offset:1024
	ds_read_b128 v[138:141], v142 offset:2048
	ds_read_b128 v[142:145], v142 offset:3072
	ds_read_b128 v[146:149], v158
	ds_read_b128 v[150:153], v158 offset:1024
	ds_read_b128 v[154:157], v158 offset:2048
	ds_read_b128 v[158:161], v158 offset:3072
	s_add_u32 s46, s46, 0x80000
	s_addc_u32 s47, s47, 0
	s_mov_b32 m0, s53
	v_lshl_add_u64 v[238:239], s[46:47], 0, v[180:181]
	ds_read_b128 v[162:165], v221 offset:32768
	ds_read_b128 v[166:169], v221 offset:33792
	ds_read_b128 v[170:173], v221 offset:34816
	ds_read_b128 v[174:177], v221 offset:35840
	ds_read_b128 v[206:209], v221 offset:36864
	ds_read_b128 v[210:213], v221 offset:37888
	ds_read_b128 v[224:227], v221 offset:38912
	ds_read_b128 v[228:231], v221 offset:39936
	global_load_lds_dwordx4 v[238:239], off
	v_lshl_add_u64 v[238:239], s[46:47], 0, v[184:185]
	s_mov_b32 m0, s54
	s_nop 0
	global_load_lds_dwordx4 v[238:239], off
	s_waitcnt vmcnt(8)
	s_waitcnt lgkmcnt(0)
	s_barrier
	s_setprio 1
	s_waitcnt lgkmcnt(0)
	v_mfma_i32_16x16x64_i8 v[126:129], v[130:133], v[162:165], v[126:129]
	v_mfma_i32_16x16x64_i8 v[62:65], v[138:141], v[162:165], v[62:65]
	v_mfma_i32_16x16x64_i8 v[118:121], v[130:133], v[170:173], v[118:121]
	v_mfma_i32_16x16x64_i8 v[54:57], v[138:141], v[170:173], v[54:57]
	v_mfma_i32_16x16x64_i8 v[110:113], v[130:133], v[206:209], v[110:113]
	v_mfma_i32_16x16x64_i8 v[46:49], v[138:141], v[206:209], v[46:49]
	v_mfma_i32_16x16x64_i8 v[102:105], v[130:133], v[224:227], v[102:105]
	v_mfma_i32_16x16x64_i8 v[38:41], v[138:141], v[224:227], v[38:41]
	v_mfma_i32_16x16x64_i8 v[126:129], v[134:137], v[166:169], v[126:129]
	v_mfma_i32_16x16x64_i8 v[62:65], v[142:145], v[166:169], v[62:65]
	v_mfma_i32_16x16x64_i8 v[118:121], v[134:137], v[174:177], v[118:121]
	v_mfma_i32_16x16x64_i8 v[54:57], v[142:145], v[174:177], v[54:57]
	v_mfma_i32_16x16x64_i8 v[110:113], v[134:137], v[210:213], v[110:113]
	v_mfma_i32_16x16x64_i8 v[46:49], v[142:145], v[210:213], v[46:49]
	v_mfma_i32_16x16x64_i8 v[102:105], v[134:137], v[228:231], v[102:105]
	v_mfma_i32_16x16x64_i8 v[38:41], v[142:145], v[228:231], v[38:41]
	s_setprio 0
	s_setprio 1
	v_mfma_i32_16x16x64_i8 v[122:125], v[146:149], v[162:165], v[122:125]
	v_mfma_i32_16x16x64_i8 v[58:61], v[154:157], v[162:165], v[58:61]
	v_mfma_i32_16x16x64_i8 v[114:117], v[146:149], v[170:173], v[114:117]
	v_mfma_i32_16x16x64_i8 v[50:53], v[154:157], v[170:173], v[50:53]
	v_mfma_i32_16x16x64_i8 v[106:109], v[146:149], v[206:209], v[106:109]
	v_mfma_i32_16x16x64_i8 v[42:45], v[154:157], v[206:209], v[42:45]
	v_mfma_i32_16x16x64_i8 v[98:101], v[146:149], v[224:227], v[98:101]
	v_mfma_i32_16x16x64_i8 v[34:37], v[154:157], v[224:227], v[34:37]
	v_mfma_i32_16x16x64_i8 v[122:125], v[150:153], v[166:169], v[122:125]
	v_mfma_i32_16x16x64_i8 v[58:61], v[158:161], v[166:169], v[58:61]
	v_mfma_i32_16x16x64_i8 v[114:117], v[150:153], v[174:177], v[114:117]
	v_mfma_i32_16x16x64_i8 v[50:53], v[158:161], v[174:177], v[50:53]
	v_mfma_i32_16x16x64_i8 v[106:109], v[150:153], v[210:213], v[106:109]
	v_mfma_i32_16x16x64_i8 v[42:45], v[158:161], v[210:213], v[42:45]
	v_mfma_i32_16x16x64_i8 v[98:101], v[150:153], v[228:231], v[98:101]
	v_mfma_i32_16x16x64_i8 v[34:37], v[158:161], v[228:231], v[34:37]
	s_setprio 0
	s_barrier
	s_add_i32 s46, s75, s50
	v_lshl_add_u64 v[178:179], v[178:179], 0, s[18:19]
	s_mov_b32 m0, s46
	ds_read_b128 v[162:165], v221 offset:49152
	ds_read_b128 v[166:169], v221 offset:50176
	ds_read_b128 v[170:173], v221 offset:51200
	ds_read_b128 v[174:177], v221 offset:52224
	ds_read_b128 v[206:209], v221 offset:53248
	ds_read_b128 v[210:213], v221 offset:54272
	ds_read_b128 v[224:227], v221 offset:55296
	ds_read_b128 v[228:231], v221 offset:56320
	global_load_lds_dwordx4 v[178:179], off
	s_add_i32 m0, s46, 0x2000
	s_add_u32 s44, s44, 0x80080
	v_lshl_add_u64 v[178:179], v[232:233], 0, s[18:19]
	s_addc_u32 s45, s45, 0
	s_add_i32 s46, s76, s50
	global_load_lds_dwordx4 v[178:179], off
	v_lshl_add_u64 v[178:179], s[44:45], 0, v[182:183]
	s_mov_b32 m0, s46
	s_nop 0
	global_load_lds_dwordx4 v[178:179], off
	v_lshl_add_u64 v[178:179], s[44:45], 0, v[186:187]
	s_add_i32 m0, s46, 0x2000
	s_nop 0
	global_load_lds_dwordx4 v[178:179], off
	v_lshl_add_u64 v[178:179], v[234:235], 0, s[18:19]
	s_mov_b32 m0, s61
	s_nop 0
	global_load_lds_dwordx4 v[178:179], off
	v_lshl_add_u64 v[178:179], v[236:237], 0, s[18:19]
	s_mov_b32 m0, s68
	s_nop 0
	global_load_lds_dwordx4 v[178:179], off
	s_waitcnt vmcnt(8)
	s_waitcnt lgkmcnt(0)
	s_barrier
	s_setprio 1
	s_waitcnt lgkmcnt(0)
	v_mfma_i32_16x16x64_i8 v[94:97], v[130:133], v[162:165], v[94:97]
	v_mfma_i32_16x16x64_i8 v[30:33], v[138:141], v[162:165], v[30:33]
	v_mfma_i32_16x16x64_i8 v[86:89], v[130:133], v[170:173], v[86:89]
	v_mfma_i32_16x16x64_i8 v[22:25], v[138:141], v[170:173], v[22:25]
	v_mfma_i32_16x16x64_i8 v[78:81], v[130:133], v[206:209], v[78:81]
	v_mfma_i32_16x16x64_i8 v[14:17], v[138:141], v[206:209], v[14:17]
	v_mfma_i32_16x16x64_i8 v[70:73], v[130:133], v[224:227], v[70:73]
	v_mfma_i32_16x16x64_i8 v[6:9], v[138:141], v[224:227], v[6:9]
	v_mfma_i32_16x16x64_i8 v[94:97], v[134:137], v[166:169], v[94:97]
	v_mfma_i32_16x16x64_i8 v[30:33], v[142:145], v[166:169], v[30:33]
	v_mfma_i32_16x16x64_i8 v[86:89], v[134:137], v[174:177], v[86:89]
	v_mfma_i32_16x16x64_i8 v[22:25], v[142:145], v[174:177], v[22:25]
	v_mfma_i32_16x16x64_i8 v[78:81], v[134:137], v[210:213], v[78:81]
	v_mfma_i32_16x16x64_i8 v[14:17], v[142:145], v[210:213], v[14:17]
	v_mfma_i32_16x16x64_i8 v[70:73], v[134:137], v[228:231], v[70:73]
	v_mfma_i32_16x16x64_i8 v[6:9], v[142:145], v[228:231], v[6:9]
	s_setprio 0
	s_setprio 1
	v_mfma_i32_16x16x64_i8 v[90:93], v[146:149], v[162:165], v[90:93]
	v_mfma_i32_16x16x64_i8 v[26:29], v[154:157], v[162:165], v[26:29]
	v_mfma_i32_16x16x64_i8 v[82:85], v[146:149], v[170:173], v[82:85]
	v_mfma_i32_16x16x64_i8 v[18:21], v[154:157], v[170:173], v[18:21]
	v_mfma_i32_16x16x64_i8 v[74:77], v[146:149], v[206:209], v[74:77]
	v_mfma_i32_16x16x64_i8 v[10:13], v[154:157], v[206:209], v[10:13]
	v_mfma_i32_16x16x64_i8 v[66:69], v[146:149], v[224:227], v[66:69]
	v_mfma_i32_16x16x64_i8 v[2:5], v[154:157], v[224:227], v[2:5]
	v_mfma_i32_16x16x64_i8 v[90:93], v[150:153], v[166:169], v[90:93]
	v_mfma_i32_16x16x64_i8 v[26:29], v[158:161], v[166:169], v[26:29]
	v_mfma_i32_16x16x64_i8 v[82:85], v[150:153], v[174:177], v[82:85]
	v_mfma_i32_16x16x64_i8 v[18:21], v[158:161], v[174:177], v[18:21]
	v_mfma_i32_16x16x64_i8 v[74:77], v[150:153], v[210:213], v[74:77]
	v_mfma_i32_16x16x64_i8 v[10:13], v[158:161], v[210:213], v[10:13]
	v_mfma_i32_16x16x64_i8 v[66:69], v[150:153], v[228:231], v[66:69]
	v_mfma_i32_16x16x64_i8 v[2:5], v[158:161], v[228:231], v[2:5]
	s_setprio 0
	s_add_i32 s74, s74, 2
	s_add_u32 s42, s42, 0x100
	s_addc_u32 s43, s43, 0
	s_add_u32 s41, s41, 0x100
	s_addc_u32 s73, s73, 0
	s_cmp_gt_u32 s74, 29
	s_barrier
	s_cbranch_scc0 .LBB0_1876
	s_load_dword s94, s[16:17], 0x0
	v_lshl_or_b32 v248, s40, 7, v194
	v_mov_b32_e32 v249, 0
	s_lshl_b32 s96, s40, 10
	s_mov_b32 s97, 0
	v_lshlrev_b64 v[248:249], 2, v[248:249]
	v_lshl_add_u64 v[244:245], v[196:197], 0, s[96:97]
	v_lshl_add_u64 v[240:241], s[56:57], 0, v[248:249]
	v_lshl_add_u64 v[242:243], s[58:59], 0, v[248:249]
	global_load_dwordx4 v[176:179], v[244:245], off
	global_load_dwordx4 v[232:235], v[244:245], off offset:16
	global_load_dwordx4 v[160:163], v[244:245], off offset:512
	global_load_dwordx4 v[236:239], v[244:245], off offset:528
	global_load_dwordx4 v[224:227], v[242:243], off
	global_load_dwordx4 v[148:151], v[240:241], off
	s_mov_b32 s96, 0xac00
	v_lshl_add_u64 v[246:247], v[242:243], 0, s[96:97]
	global_load_dwordx4 v[228:231], v[246:247], off
	s_mov_b32 s96, 0xac00
	v_lshl_add_u64 v[246:247], v[240:241], 0, s[96:97]
	global_load_dwordx4 v[168:171], v[246:247], off
	s_mov_b32 s96, 0x15800
	v_lshl_add_u64 v[246:247], v[240:241], 0, s[96:97]
	global_load_dwordx4 v[156:159], v[246:247], off
	s_mov_b32 s96, 0x20400
	v_lshl_add_u64 v[246:247], v[240:241], 0, s[96:97]
	global_load_dwordx4 v[164:167], v[246:247], off
	s_mov_b32 s96, 0x2b000
	v_lshl_add_u64 v[246:247], v[240:241], 0, s[96:97]
	global_load_dwordx4 v[152:155], v[246:247], off
	s_mov_b32 s96, 0x35c00
	v_lshl_add_u64 v[246:247], v[240:241], 0, s[96:97]
	global_load_dwordx4 v[172:175], v[246:247], off
	s_and_b64 vcc, exec, s[20:21]
	s_cbranch_vccz .LBB0_1879
	s_barrier

.LBB0_2040:
	ds_read_b128 v[146:149], v154
	ds_read_b128 v[158:161], v154 offset:1024
	ds_read_b128 v[162:165], v154 offset:2048
	ds_read_b128 v[166:169], v154 offset:3072
	ds_read_b128 v[170:173], v155
	ds_read_b128 v[174:177], v155 offset:1024
	ds_read_b128 v[178:181], v155 offset:2048
	ds_read_b128 v[182:185], v155 offset:3072
	s_add_u32 s28, s26, 0xffd50080
	s_addc_u32 s29, s27, -1
	s_cmpk_eq_i32 s54, 0xa8
	s_cselect_b32 s31, s7, s29
	s_cselect_b32 s30, s6, s28
	s_cselect_b32 s29, s25, s53
	s_cselect_b32 s28, s24, s52
	v_lshl_add_u64 v[150:151], s[26:27], 0, v[138:139]
	s_add_i32 m0, s38, 0xc000
	ds_read_b128 v[186:189], v156
	ds_read_b128 v[190:193], v156 offset:1024
	ds_read_b128 v[194:197], v156 offset:2048
	ds_read_b128 v[198:201], v156 offset:3072
	ds_read_b128 v[202:205], v156 offset:4096
	ds_read_b128 v[206:209], v156 offset:5120
	ds_read_b128 v[210:213], v156 offset:6144
	ds_read_b128 v[214:217], v156 offset:7168
	global_load_lds_dwordx4 v[150:151], off
	v_lshl_add_u64 v[150:151], s[26:27], 0, v[140:141]
	s_add_i32 m0, s38, 0xe000
	s_nop 0
	global_load_lds_dwordx4 v[150:151], off
	s_waitcnt vmcnt(8)
	s_waitcnt lgkmcnt(0)
	s_barrier
	s_setprio 1
	s_waitcnt lgkmcnt(0)
	v_mfma_f32_16x16x32_bf16 v[126:129], v[146:149], v[186:189], v[126:129]
	v_mfma_f32_16x16x32_bf16 v[122:125], v[162:165], v[186:189], v[122:125]
	v_mfma_f32_16x16x32_bf16 v[114:117], v[146:149], v[194:197], v[114:117]
	v_mfma_f32_16x16x32_bf16 v[106:109], v[162:165], v[194:197], v[106:109]
	v_mfma_f32_16x16x32_bf16 v[98:101], v[146:149], v[202:205], v[98:101]
	v_mfma_f32_16x16x32_bf16 v[90:93], v[162:165], v[202:205], v[90:93]
	v_mfma_f32_16x16x32_bf16 v[82:85], v[146:149], v[210:213], v[82:85]
	v_mfma_f32_16x16x32_bf16 v[74:77], v[162:165], v[210:213], v[74:77]
	v_mfma_f32_16x16x32_bf16 v[126:129], v[158:161], v[190:193], v[126:129]
	v_mfma_f32_16x16x32_bf16 v[122:125], v[166:169], v[190:193], v[122:125]
	v_mfma_f32_16x16x32_bf16 v[114:117], v[158:161], v[198:201], v[114:117]
	v_mfma_f32_16x16x32_bf16 v[106:109], v[166:169], v[198:201], v[106:109]
	v_mfma_f32_16x16x32_bf16 v[98:101], v[158:161], v[206:209], v[98:101]
	v_mfma_f32_16x16x32_bf16 v[90:93], v[166:169], v[206:209], v[90:93]
	v_mfma_f32_16x16x32_bf16 v[82:85], v[158:161], v[214:217], v[82:85]
	v_mfma_f32_16x16x32_bf16 v[74:77], v[166:169], v[214:217], v[74:77]
	s_setprio 0
	s_setprio 1
	v_mfma_f32_16x16x32_bf16 v[118:121], v[170:173], v[186:189], v[118:121]
	v_mfma_f32_16x16x32_bf16 v[110:113], v[178:181], v[186:189], v[110:113]
	v_mfma_f32_16x16x32_bf16 v[102:105], v[170:173], v[194:197], v[102:105]
	v_mfma_f32_16x16x32_bf16 v[94:97], v[178:181], v[194:197], v[94:97]
	v_mfma_f32_16x16x32_bf16 v[86:89], v[170:173], v[202:205], v[86:89]
	v_mfma_f32_16x16x32_bf16 v[78:81], v[178:181], v[202:205], v[78:81]
	v_mfma_f32_16x16x32_bf16 v[70:73], v[170:173], v[210:213], v[70:73]
	v_mfma_f32_16x16x32_bf16 v[66:69], v[178:181], v[210:213], v[66:69]
	v_mfma_f32_16x16x32_bf16 v[118:121], v[174:177], v[190:193], v[118:121]
	v_mfma_f32_16x16x32_bf16 v[110:113], v[182:185], v[190:193], v[110:113]
	v_mfma_f32_16x16x32_bf16 v[102:105], v[174:177], v[198:201], v[102:105]
	v_mfma_f32_16x16x32_bf16 v[94:97], v[182:185], v[198:201], v[94:97]
	v_mfma_f32_16x16x32_bf16 v[86:89], v[174:177], v[206:209], v[86:89]
	v_mfma_f32_16x16x32_bf16 v[78:81], v[182:185], v[206:209], v[78:81]
	v_mfma_f32_16x16x32_bf16 v[70:73], v[174:177], v[214:217], v[70:73]
	v_mfma_f32_16x16x32_bf16 v[66:69], v[182:185], v[214:217], v[66:69]
	s_setprio 0
	s_barrier
	s_add_i32 s55, s46, s37
	v_lshl_add_u64 v[150:151], s[28:29], 0, v[132:133]
	s_mov_b32 m0, s55
	ds_read_b128 v[186:189], v156 offset:16384
	ds_read_b128 v[190:193], v156 offset:17408
	ds_read_b128 v[194:197], v156 offset:18432
	ds_read_b128 v[198:201], v156 offset:19456
	ds_read_b128 v[202:205], v156 offset:20480
	ds_read_b128 v[206:209], v156 offset:21504
	ds_read_b128 v[210:213], v156 offset:22528
	ds_read_b128 v[214:217], v156 offset:23552
	global_load_lds_dwordx4 v[150:151], off
	s_add_i32 m0, s55, 0x2000
	s_add_u32 s56, s28, 0x2b0000
	v_lshl_add_u64 v[218:219], s[28:29], 0, v[136:137]
	s_addc_u32 s57, s29, 0
	s_add_i32 s55, s47, s37
	global_load_lds_dwordx4 v[218:219], off
	v_lshl_add_u64 v[220:221], s[56:57], 0, v[132:133]
	s_mov_b32 m0, s55
	v_lshl_add_u64 v[222:223], s[30:31], 0, v[134:135]
	global_load_lds_dwordx4 v[220:221], off
	v_lshl_add_u64 v[220:221], s[56:57], 0, v[136:137]
	s_add_i32 m0, s55, 0x2000
	s_nop 0
	global_load_lds_dwordx4 v[220:221], off
	v_lshl_add_u64 v[220:221], s[30:31], 0, v[130:131]
	s_mov_b32 m0, s38
	s_nop 0
	global_load_lds_dwordx4 v[220:221], off
	s_mov_b32 m0, s39
	s_nop 0
	global_load_lds_dwordx4 v[222:223], off
	s_waitcnt vmcnt(8)
	s_waitcnt lgkmcnt(0)
	s_barrier
	s_setprio 1
	s_waitcnt lgkmcnt(0)
	v_mfma_f32_16x16x32_bf16 v[62:65], v[146:149], v[186:189], v[62:65]
	v_mfma_f32_16x16x32_bf16 v[58:61], v[162:165], v[186:189], v[58:61]
	v_mfma_f32_16x16x32_bf16 v[50:53], v[146:149], v[194:197], v[50:53]
	v_mfma_f32_16x16x32_bf16 v[42:45], v[162:165], v[194:197], v[42:45]
	v_mfma_f32_16x16x32_bf16 v[34:37], v[146:149], v[202:205], v[34:37]
	v_mfma_f32_16x16x32_bf16 v[26:29], v[162:165], v[202:205], v[26:29]
	v_mfma_f32_16x16x32_bf16 v[18:21], v[146:149], v[210:213], v[18:21]
	v_mfma_f32_16x16x32_bf16 v[10:13], v[162:165], v[210:213], v[10:13]
	v_mfma_f32_16x16x32_bf16 v[62:65], v[158:161], v[190:193], v[62:65]
	v_mfma_f32_16x16x32_bf16 v[58:61], v[166:169], v[190:193], v[58:61]
	v_mfma_f32_16x16x32_bf16 v[50:53], v[158:161], v[198:201], v[50:53]
	v_mfma_f32_16x16x32_bf16 v[42:45], v[166:169], v[198:201], v[42:45]
	v_mfma_f32_16x16x32_bf16 v[34:37], v[158:161], v[206:209], v[34:37]
	v_mfma_f32_16x16x32_bf16 v[26:29], v[166:169], v[206:209], v[26:29]
	v_mfma_f32_16x16x32_bf16 v[18:21], v[158:161], v[214:217], v[18:21]
	v_mfma_f32_16x16x32_bf16 v[10:13], v[166:169], v[214:217], v[10:13]
	s_setprio 0
	s_setprio 1
	v_mfma_f32_16x16x32_bf16 v[54:57], v[170:173], v[186:189], v[54:57]
	v_mfma_f32_16x16x32_bf16 v[46:49], v[178:181], v[186:189], v[46:49]
	v_mfma_f32_16x16x32_bf16 v[38:41], v[170:173], v[194:197], v[38:41]
	v_mfma_f32_16x16x32_bf16 v[30:33], v[178:181], v[194:197], v[30:33]
	v_mfma_f32_16x16x32_bf16 v[22:25], v[170:173], v[202:205], v[22:25]
	v_mfma_f32_16x16x32_bf16 v[14:17], v[178:181], v[202:205], v[14:17]
	v_mfma_f32_16x16x32_bf16 v[6:9], v[170:173], v[210:213], v[6:9]
	v_mfma_f32_16x16x32_bf16 v[2:5], v[178:181], v[210:213], v[2:5]
	v_mfma_f32_16x16x32_bf16 v[54:57], v[174:177], v[190:193], v[54:57]
	v_mfma_f32_16x16x32_bf16 v[46:49], v[182:185], v[190:193], v[46:49]
	v_mfma_f32_16x16x32_bf16 v[38:41], v[174:177], v[198:201], v[38:41]
	v_mfma_f32_16x16x32_bf16 v[30:33], v[182:185], v[198:201], v[30:33]
	v_mfma_f32_16x16x32_bf16 v[22:25], v[174:177], v[206:209], v[22:25]
	v_mfma_f32_16x16x32_bf16 v[14:17], v[182:185], v[206:209], v[14:17]
	v_mfma_f32_16x16x32_bf16 v[6:9], v[174:177], v[214:217], v[6:9]
	v_mfma_f32_16x16x32_bf16 v[2:5], v[182:185], v[214:217], v[2:5]
	s_setprio 0
	s_barrier
	s_add_i32 s55, 0, 0x18000
	v_add_u32_e32 v157, s55, v152
	s_add_i32 s56, 0, 0x1c000
	ds_read_b128 v[146:149], v157
	ds_read_b128 v[158:161], v157 offset:1024
	ds_read_b128 v[162:165], v157 offset:2048
	ds_read_b128 v[166:169], v157 offset:3072
	v_add_u32_e32 v157, s56, v152
	ds_read_b128 v[170:173], v157
	ds_read_b128 v[174:177], v157 offset:1024
	ds_read_b128 v[178:181], v157 offset:2048
	ds_read_b128 v[182:185], v157 offset:3072
	s_add_u32 s30, s30, 0x2b0000
	s_addc_u32 s31, s31, 0
	s_mov_b32 m0, s40
	v_lshl_add_u64 v[224:225], s[30:31], 0, v[130:131]
	ds_read_b128 v[186:189], v156 offset:32768
	ds_read_b128 v[190:193], v156 offset:33792
	ds_read_b128 v[194:197], v156 offset:34816
	ds_read_b128 v[198:201], v156 offset:35840
	ds_read_b128 v[202:205], v156 offset:36864
	ds_read_b128 v[206:209], v156 offset:37888
	ds_read_b128 v[210:213], v156 offset:38912
	ds_read_b128 v[214:217], v156 offset:39936
	global_load_lds_dwordx4 v[224:225], off
	v_lshl_add_u64 v[224:225], s[30:31], 0, v[134:135]
	s_mov_b32 m0, s41
	s_nop 0
	global_load_lds_dwordx4 v[224:225], off
	s_waitcnt vmcnt(8)
	s_waitcnt lgkmcnt(0)
	s_barrier
	s_setprio 1
	s_waitcnt lgkmcnt(0)
	v_mfma_f32_16x16x32_bf16 v[126:129], v[146:149], v[186:189], v[126:129]
	v_mfma_f32_16x16x32_bf16 v[122:125], v[162:165], v[186:189], v[122:125]
	v_mfma_f32_16x16x32_bf16 v[114:117], v[146:149], v[194:197], v[114:117]
	v_mfma_f32_16x16x32_bf16 v[106:109], v[162:165], v[194:197], v[106:109]
	v_mfma_f32_16x16x32_bf16 v[98:101], v[146:149], v[202:205], v[98:101]
	v_mfma_f32_16x16x32_bf16 v[90:93], v[162:165], v[202:205], v[90:93]
	v_mfma_f32_16x16x32_bf16 v[82:85], v[146:149], v[210:213], v[82:85]
	v_mfma_f32_16x16x32_bf16 v[74:77], v[162:165], v[210:213], v[74:77]
	v_mfma_f32_16x16x32_bf16 v[126:129], v[158:161], v[190:193], v[126:129]
	v_mfma_f32_16x16x32_bf16 v[122:125], v[166:169], v[190:193], v[122:125]
	v_mfma_f32_16x16x32_bf16 v[114:117], v[158:161], v[198:201], v[114:117]
	v_mfma_f32_16x16x32_bf16 v[106:109], v[166:169], v[198:201], v[106:109]
	v_mfma_f32_16x16x32_bf16 v[98:101], v[158:161], v[206:209], v[98:101]
	v_mfma_f32_16x16x32_bf16 v[90:93], v[166:169], v[206:209], v[90:93]
	v_mfma_f32_16x16x32_bf16 v[82:85], v[158:161], v[214:217], v[82:85]
	v_mfma_f32_16x16x32_bf16 v[74:77], v[166:169], v[214:217], v[74:77]
	s_setprio 0
	s_setprio 1
	v_mfma_f32_16x16x32_bf16 v[118:121], v[170:173], v[186:189], v[118:121]
	v_mfma_f32_16x16x32_bf16 v[110:113], v[178:181], v[186:189], v[110:113]
	v_mfma_f32_16x16x32_bf16 v[102:105], v[170:173], v[194:197], v[102:105]
	v_mfma_f32_16x16x32_bf16 v[94:97], v[178:181], v[194:197], v[94:97]
	v_mfma_f32_16x16x32_bf16 v[86:89], v[170:173], v[202:205], v[86:89]
	v_mfma_f32_16x16x32_bf16 v[78:81], v[178:181], v[202:205], v[78:81]
	v_mfma_f32_16x16x32_bf16 v[70:73], v[170:173], v[210:213], v[70:73]
	v_mfma_f32_16x16x32_bf16 v[66:69], v[178:181], v[210:213], v[66:69]
	v_mfma_f32_16x16x32_bf16 v[118:121], v[174:177], v[190:193], v[118:121]
	v_mfma_f32_16x16x32_bf16 v[110:113], v[182:185], v[190:193], v[110:113]
	v_mfma_f32_16x16x32_bf16 v[102:105], v[174:177], v[198:201], v[102:105]
	v_mfma_f32_16x16x32_bf16 v[94:97], v[182:185], v[198:201], v[94:97]
	v_mfma_f32_16x16x32_bf16 v[86:89], v[174:177], v[206:209], v[86:89]
	v_mfma_f32_16x16x32_bf16 v[78:81], v[182:185], v[206:209], v[78:81]
	v_mfma_f32_16x16x32_bf16 v[70:73], v[174:177], v[214:217], v[70:73]
	v_mfma_f32_16x16x32_bf16 v[66:69], v[182:185], v[214:217], v[66:69]
	s_setprio 0
	s_barrier
	s_add_i32 s30, s55, s37
	v_lshl_add_u64 v[150:151], v[150:151], 0, s[12:13]
	s_mov_b32 m0, s30
	ds_read_b128 v[186:189], v156 offset:49152
	ds_read_b128 v[190:193], v156 offset:50176
	ds_read_b128 v[194:197], v156 offset:51200
	ds_read_b128 v[198:201], v156 offset:52224
	ds_read_b128 v[202:205], v156 offset:53248
	ds_read_b128 v[206:209], v156 offset:54272
	ds_read_b128 v[210:213], v156 offset:55296
	ds_read_b128 v[214:217], v156 offset:56320
	global_load_lds_dwordx4 v[150:151], off
	s_add_i32 m0, s30, 0x2000
	s_add_u32 s28, s28, 0x2b0080
	v_lshl_add_u64 v[150:151], v[218:219], 0, s[12:13]
	s_addc_u32 s29, s29, 0
	s_add_i32 s30, s56, s37
	global_load_lds_dwordx4 v[150:151], off
	v_lshl_add_u64 v[150:151], s[28:29], 0, v[132:133]
	s_mov_b32 m0, s30
	s_nop 0
	global_load_lds_dwordx4 v[150:151], off
	v_lshl_add_u64 v[150:151], s[28:29], 0, v[136:137]
	s_add_i32 m0, s30, 0x2000
	s_nop 0
	global_load_lds_dwordx4 v[150:151], off
	v_lshl_add_u64 v[150:151], v[220:221], 0, s[12:13]
	s_mov_b32 m0, s44
	s_nop 0
	global_load_lds_dwordx4 v[150:151], off
	v_lshl_add_u64 v[150:151], v[222:223], 0, s[12:13]
	s_mov_b32 m0, s45
	s_nop 0
	global_load_lds_dwordx4 v[150:151], off
	s_waitcnt vmcnt(8)
	s_waitcnt lgkmcnt(0)
	s_barrier
	s_setprio 1
	s_waitcnt lgkmcnt(0)
	v_mfma_f32_16x16x32_bf16 v[62:65], v[146:149], v[186:189], v[62:65]
	v_mfma_f32_16x16x32_bf16 v[58:61], v[162:165], v[186:189], v[58:61]
	v_mfma_f32_16x16x32_bf16 v[50:53], v[146:149], v[194:197], v[50:53]
	v_mfma_f32_16x16x32_bf16 v[42:45], v[162:165], v[194:197], v[42:45]
	v_mfma_f32_16x16x32_bf16 v[34:37], v[146:149], v[202:205], v[34:37]
	v_mfma_f32_16x16x32_bf16 v[26:29], v[162:165], v[202:205], v[26:29]
	v_mfma_f32_16x16x32_bf16 v[18:21], v[146:149], v[210:213], v[18:21]
	v_mfma_f32_16x16x32_bf16 v[10:13], v[162:165], v[210:213], v[10:13]
	v_mfma_f32_16x16x32_bf16 v[62:65], v[158:161], v[190:193], v[62:65]
	v_mfma_f32_16x16x32_bf16 v[58:61], v[166:169], v[190:193], v[58:61]
	v_mfma_f32_16x16x32_bf16 v[50:53], v[158:161], v[198:201], v[50:53]
	v_mfma_f32_16x16x32_bf16 v[42:45], v[166:169], v[198:201], v[42:45]
	v_mfma_f32_16x16x32_bf16 v[34:37], v[158:161], v[206:209], v[34:37]
	v_mfma_f32_16x16x32_bf16 v[26:29], v[166:169], v[206:209], v[26:29]
	v_mfma_f32_16x16x32_bf16 v[18:21], v[158:161], v[214:217], v[18:21]
	v_mfma_f32_16x16x32_bf16 v[10:13], v[166:169], v[214:217], v[10:13]
	s_setprio 0
	s_setprio 1
	v_mfma_f32_16x16x32_bf16 v[54:57], v[170:173], v[186:189], v[54:57]
	v_mfma_f32_16x16x32_bf16 v[46:49], v[178:181], v[186:189], v[46:49]
	v_mfma_f32_16x16x32_bf16 v[38:41], v[170:173], v[194:197], v[38:41]
	v_mfma_f32_16x16x32_bf16 v[30:33], v[178:181], v[194:197], v[30:33]
	v_mfma_f32_16x16x32_bf16 v[22:25], v[170:173], v[202:205], v[22:25]
	v_mfma_f32_16x16x32_bf16 v[14:17], v[178:181], v[202:205], v[14:17]
	v_mfma_f32_16x16x32_bf16 v[6:9], v[170:173], v[210:213], v[6:9]
	v_mfma_f32_16x16x32_bf16 v[2:5], v[178:181], v[210:213], v[2:5]
	v_mfma_f32_16x16x32_bf16 v[54:57], v[174:177], v[190:193], v[54:57]
	v_mfma_f32_16x16x32_bf16 v[46:49], v[182:185], v[190:193], v[46:49]
	v_mfma_f32_16x16x32_bf16 v[38:41], v[174:177], v[198:201], v[38:41]
	v_mfma_f32_16x16x32_bf16 v[30:33], v[182:185], v[198:201], v[30:33]
	v_mfma_f32_16x16x32_bf16 v[22:25], v[174:177], v[206:209], v[22:25]
	v_mfma_f32_16x16x32_bf16 v[14:17], v[182:185], v[206:209], v[14:17]
	v_mfma_f32_16x16x32_bf16 v[6:9], v[174:177], v[214:217], v[6:9]
	v_mfma_f32_16x16x32_bf16 v[2:5], v[182:185], v[214:217], v[2:5]
	s_setprio 0
	s_add_i32 s54, s54, 2
	s_add_u32 s26, s26, 0x100
	s_addc_u32 s27, s27, 0
	s_add_u32 s52, s52, 0x100
	s_addc_u32 s53, s53, 0
	s_cmpk_gt_u32 s54, 0xa9
	s_barrier
	s_cbranch_scc0 .LBB0_2040
	s_and_b64 vcc, exec, s[14:15]
	s_cbranch_vccz .LBB0_2043
	s_barrier
